# P0 weight transposes: w_ffn_in item loads batched (was one element per vmcnt(0)); both 16-load rounds of every transpose item issued back to back
# speedup vs baseline: 1.0305x; 1.0034x over previous
.LBB0_15:
	s_lshl_b32 s29, s16, 1
	s_lshl_b32 s41, s27, 1
	v_or_b32_e32 v25, s29, v1
	v_or_b32_e32 v60, s41, v4
	s_add_i32 s43, s41, 4
	s_add_i32 s42, s29, 4
	s_add_i32 s44, s29, 8
	s_add_i32 s45, s41, 8
	s_add_i32 s46, s29, 12
	s_add_i32 s49, s29, 16
	s_add_i32 s51, s29, 20
	s_add_i32 s53, s29, 24
	s_add_i32 s29, s29, 28
	v_add_lshl_u32 v8, v25, s26, 10
	v_add_lshl_u32 v28, v60, s5, 10
	v_or_b32_e32 v62, s43, v4
	s_add_i32 s47, s41, 12
	v_or_b32_e32 v61, s42, v1
	v_or_b32_e32 v63, s44, v1
	v_or_b32_e32 v64, s45, v4
	v_or_b32_e32 v65, s46, v1
	v_or_b32_e32 v67, s49, v1
	v_or_b32_e32 v69, s51, v1
	v_or_b32_e32 v71, s53, v1
	v_or_b32_e32 v73, s29, v1
	v_or_b32_e32 v26, v5, v8
	v_or_b32_e32 v8, v24, v28
	v_add_lshl_u32 v30, v62, s5, 10
	v_mov_b32_e32 v27, v9
	s_add_i32 s50, s41, 16
	v_or_b32_e32 v66, s47, v4
	v_add_lshl_u32 v28, v61, s26, 10
	v_add_lshl_u32 v32, v63, s26, 10
	v_add_lshl_u32 v75, v64, s5, 10
	v_add_lshl_u32 v34, v65, s26, 10
	v_add_lshl_u32 v36, v67, s26, 10
	v_add_lshl_u32 v38, v69, s26, 10
	v_add_lshl_u32 v40, v71, s26, 10
	v_add_lshl_u32 v58, v73, s26, 10
	v_lshl_add_u64 v[42:43], v[8:9], 2, s[18:19]
	v_or_b32_e32 v8, v24, v30
	v_mov_b32_e32 v29, v9
	s_add_i32 s52, s41, 20
	v_or_b32_e32 v68, s50, v4
	v_add_lshl_u32 v76, v66, s5, 10
	v_lshl_add_u64 v[26:27], v[26:27], 2, s[18:19]
	v_or_b32_e32 v28, v5, v28
	v_or_b32_e32 v30, v5, v32
	v_or_b32_e32 v32, v5, v34
	v_or_b32_e32 v34, v5, v36
	v_or_b32_e32 v36, v5, v38
	v_or_b32_e32 v38, v5, v40
	v_or_b32_e32 v40, v5, v58
	v_lshl_add_u64 v[58:59], v[8:9], 2, s[18:19]
	v_or_b32_e32 v8, v24, v75
	s_add_i32 s54, s41, 24
	v_or_b32_e32 v70, s52, v4
	v_add_lshl_u32 v77, v68, s5, 10
	v_lshl_add_u64 v[28:29], v[28:29], 2, s[18:19]
	global_load_dword v75, v[42:43], off
	global_load_dword v81, v[26:27], off
	global_load_dword v82, v[58:59], off
	global_load_dword v83, v[28:29], off
	v_lshl_add_u64 v[26:27], v[8:9], 2, s[18:19]
	v_or_b32_e32 v8, v24, v76
	v_mov_b32_e32 v31, v9
	v_mov_b32_e32 v33, v9
	s_add_i32 s41, s41, 28
	v_or_b32_e32 v72, s54, v4
	v_add_lshl_u32 v78, v70, s5, 10
	v_lshl_add_u64 v[28:29], v[8:9], 2, s[18:19]
	v_or_b32_e32 v8, v24, v77
	v_or_b32_e32 v74, s41, v4
	v_add_lshl_u32 v79, v72, s5, 10
	v_lshl_add_u64 v[30:31], v[30:31], 2, s[18:19]
	v_lshl_add_u64 v[32:33], v[32:33], 2, s[18:19]
	global_load_dword v76, v[26:27], off
	global_load_dword v77, v[30:31], off
	global_load_dword v84, v[28:29], off
	global_load_dword v85, v[32:33], off
	v_lshl_add_u64 v[26:27], v[8:9], 2, s[18:19]
	v_or_b32_e32 v8, v24, v78
	v_mov_b32_e32 v35, v9
	v_mov_b32_e32 v37, v9
	v_add_lshl_u32 v80, v74, s5, 10
	v_lshl_add_u64 v[28:29], v[8:9], 2, s[18:19]
	v_or_b32_e32 v8, v24, v79
	v_mov_b32_e32 v39, v9
	v_mov_b32_e32 v41, v9
	v_lshl_add_u64 v[34:35], v[34:35], 2, s[18:19]
	v_lshl_add_u64 v[36:37], v[36:37], 2, s[18:19]
	global_load_dword v78, v[26:27], off
	global_load_dword v79, v[34:35], off
	global_load_dword v86, v[28:29], off
	global_load_dword v87, v[36:37], off
	v_lshl_add_u64 v[26:27], v[8:9], 2, s[18:19]
	v_or_b32_e32 v8, v24, v80
	v_lshl_add_u64 v[38:39], v[38:39], 2, s[18:19]
	v_lshl_add_u64 v[40:41], v[40:41], 2, s[18:19]
	v_lshl_add_u64 v[28:29], v[8:9], 2, s[18:19]
	global_load_dword v8, v[26:27], off
	global_load_dword v80, v[38:39], off
	global_load_dword v88, v[28:29], off
	global_load_dword v89, v[40:41], off
	s_add_i32 s27, s27, 16
	s_add_i32 s16, s16, 16
	s_add_i32 s28, s28, -16
	v_mad_u64_u32 v[26:27], s[42:43], v60, s36, v[6:7]
	s_cmp_lg_u32 s28, 0
	v_mad_u64_u32 v[28:29], s[42:43], v25, s36, v[6:7]
	v_mad_u64_u32 v[30:31], s[42:43], v62, s36, v[6:7]
	v_mad_u64_u32 v[32:33], s[42:43], v61, s36, v[6:7]
	v_mad_u64_u32 v[34:35], s[42:43], v64, s36, v[6:7]
	v_mad_u64_u32 v[36:37], s[42:43], v63, s36, v[6:7]
	v_mad_u64_u32 v[38:39], s[42:43], v66, s36, v[6:7]
	v_mad_u64_u32 v[40:41], s[42:43], v65, s36, v[6:7]
	v_mad_u64_u32 v[42:43], s[42:43], v68, s36, v[6:7]
	v_mad_u64_u32 v[58:59], s[42:43], v67, s36, v[6:7]
	v_mad_u64_u32 v[60:61], s[42:43], v70, s36, v[6:7]
	v_mad_u64_u32 v[62:63], s[42:43], v69, s36, v[6:7]
	v_mad_u64_u32 v[64:65], s[42:43], v72, s36, v[6:7]
	v_mad_u64_u32 v[66:67], s[42:43], v71, s36, v[6:7]
	v_mad_u64_u32 v[68:69], s[42:43], v74, s36, v[6:7]
	v_mad_u64_u32 v[70:71], s[42:43], v73, s36, v[6:7]
	v_mov_b32_e32 v109, v9
	s_lshl_b32 s29, s16, 1
	s_lshl_b32 s41, s27, 1
	v_or_b32_e32 v125, s29, v1
	v_or_b32_e32 v160, s41, v4
	s_add_i32 s43, s41, 4
	s_add_i32 s42, s29, 4
	s_add_i32 s44, s29, 8
	s_add_i32 s45, s41, 8
	s_add_i32 s46, s29, 12
	s_add_i32 s49, s29, 16
	s_add_i32 s51, s29, 20
	s_add_i32 s53, s29, 24
	s_add_i32 s29, s29, 28
	v_add_lshl_u32 v108, v125, s26, 10
	v_add_lshl_u32 v128, v160, s5, 10
	v_or_b32_e32 v162, s43, v4
	s_add_i32 s47, s41, 12
	v_or_b32_e32 v161, s42, v1
	v_or_b32_e32 v163, s44, v1
	v_or_b32_e32 v164, s45, v4
	v_or_b32_e32 v165, s46, v1
	v_or_b32_e32 v167, s49, v1
	v_or_b32_e32 v169, s51, v1
	v_or_b32_e32 v171, s53, v1
	v_or_b32_e32 v173, s29, v1
	v_or_b32_e32 v126, v5, v108
	v_or_b32_e32 v108, v24, v128
	v_add_lshl_u32 v130, v162, s5, 10
	v_mov_b32_e32 v127, v109
	s_add_i32 s50, s41, 16
	v_or_b32_e32 v166, s47, v4
	v_add_lshl_u32 v128, v161, s26, 10
	v_add_lshl_u32 v132, v163, s26, 10
	v_add_lshl_u32 v175, v164, s5, 10
	v_add_lshl_u32 v134, v165, s26, 10
	v_add_lshl_u32 v136, v167, s26, 10
	v_add_lshl_u32 v138, v169, s26, 10
	v_add_lshl_u32 v140, v171, s26, 10
	v_add_lshl_u32 v158, v173, s26, 10
	v_lshl_add_u64 v[142:143], v[108:109], 2, s[18:19]
	v_or_b32_e32 v108, v24, v130
	v_mov_b32_e32 v129, v109
	s_add_i32 s52, s41, 20
	v_or_b32_e32 v168, s50, v4
	v_add_lshl_u32 v176, v166, s5, 10
	v_lshl_add_u64 v[126:127], v[126:127], 2, s[18:19]
	v_or_b32_e32 v128, v5, v128
	v_or_b32_e32 v130, v5, v132
	v_or_b32_e32 v132, v5, v134
	v_or_b32_e32 v134, v5, v136
	v_or_b32_e32 v136, v5, v138
	v_or_b32_e32 v138, v5, v140
	v_or_b32_e32 v140, v5, v158
	v_lshl_add_u64 v[158:159], v[108:109], 2, s[18:19]
	v_or_b32_e32 v108, v24, v175
	s_add_i32 s54, s41, 24
	v_or_b32_e32 v170, s52, v4
	v_add_lshl_u32 v177, v168, s5, 10
	v_lshl_add_u64 v[128:129], v[128:129], 2, s[18:19]
	global_load_dword v175, v[142:143], off
	global_load_dword v181, v[126:127], off
	global_load_dword v182, v[158:159], off
	global_load_dword v183, v[128:129], off
	v_lshl_add_u64 v[126:127], v[108:109], 2, s[18:19]
	v_or_b32_e32 v108, v24, v176
	v_mov_b32_e32 v131, v109
	v_mov_b32_e32 v133, v109
	s_add_i32 s41, s41, 28
	v_or_b32_e32 v172, s54, v4
	v_add_lshl_u32 v178, v170, s5, 10
	v_lshl_add_u64 v[128:129], v[108:109], 2, s[18:19]
	v_or_b32_e32 v108, v24, v177
	v_or_b32_e32 v174, s41, v4
	v_add_lshl_u32 v179, v172, s5, 10
	v_lshl_add_u64 v[130:131], v[130:131], 2, s[18:19]
	v_lshl_add_u64 v[132:133], v[132:133], 2, s[18:19]
	global_load_dword v176, v[126:127], off
	global_load_dword v177, v[130:131], off
	global_load_dword v184, v[128:129], off
	global_load_dword v185, v[132:133], off
	v_lshl_add_u64 v[126:127], v[108:109], 2, s[18:19]
	v_or_b32_e32 v108, v24, v178
	v_mov_b32_e32 v135, v109
	v_mov_b32_e32 v137, v109
	v_add_lshl_u32 v180, v174, s5, 10
	v_lshl_add_u64 v[128:129], v[108:109], 2, s[18:19]
	v_or_b32_e32 v108, v24, v179
	v_mov_b32_e32 v139, v109
	v_mov_b32_e32 v141, v109
	v_lshl_add_u64 v[134:135], v[134:135], 2, s[18:19]
	v_lshl_add_u64 v[136:137], v[136:137], 2, s[18:19]
	global_load_dword v178, v[126:127], off
	global_load_dword v179, v[134:135], off
	global_load_dword v186, v[128:129], off
	global_load_dword v187, v[136:137], off
	v_lshl_add_u64 v[126:127], v[108:109], 2, s[18:19]
	v_or_b32_e32 v108, v24, v180
	v_lshl_add_u64 v[138:139], v[138:139], 2, s[18:19]
	v_lshl_add_u64 v[140:141], v[140:141], 2, s[18:19]
	v_lshl_add_u64 v[128:129], v[108:109], 2, s[18:19]
	global_load_dword v108, v[126:127], off
	global_load_dword v180, v[138:139], off
	global_load_dword v188, v[128:129], off
	global_load_dword v189, v[140:141], off
	s_add_i32 s27, s27, 16
	s_add_i32 s16, s16, 16
	s_add_i32 s28, s28, -16
	v_mad_u64_u32 v[126:127], s[42:43], v160, s36, v[6:7]
	s_cmp_lg_u32 s28, 0
	v_mad_u64_u32 v[128:129], s[42:43], v125, s36, v[6:7]
	v_mad_u64_u32 v[130:131], s[42:43], v162, s36, v[6:7]
	v_mad_u64_u32 v[132:133], s[42:43], v161, s36, v[6:7]
	v_mad_u64_u32 v[134:135], s[42:43], v164, s36, v[6:7]
	v_mad_u64_u32 v[136:137], s[42:43], v163, s36, v[6:7]
	v_mad_u64_u32 v[138:139], s[42:43], v166, s36, v[6:7]
	v_mad_u64_u32 v[140:141], s[42:43], v165, s36, v[6:7]
	v_mad_u64_u32 v[142:143], s[42:43], v168, s36, v[6:7]
	v_mad_u64_u32 v[158:159], s[42:43], v167, s36, v[6:7]
	v_mad_u64_u32 v[160:161], s[42:43], v170, s36, v[6:7]
	v_mad_u64_u32 v[162:163], s[42:43], v169, s36, v[6:7]
	v_mad_u64_u32 v[164:165], s[42:43], v172, s36, v[6:7]
	v_mad_u64_u32 v[166:167], s[42:43], v171, s36, v[6:7]
	v_mad_u64_u32 v[168:169], s[42:43], v174, s36, v[6:7]
	v_mad_u64_u32 v[170:171], s[42:43], v173, s36, v[6:7]
	s_waitcnt vmcnt(31)
	ds_write_b32 v26, v75
	s_waitcnt vmcnt(30)
	ds_write_b32 v28, v81
	s_waitcnt vmcnt(29)
	ds_write_b32 v30, v82
	s_waitcnt vmcnt(28)
	ds_write_b32 v32, v83
	s_waitcnt vmcnt(27)
	ds_write_b32 v34, v76
	s_waitcnt vmcnt(26)
	ds_write_b32 v36, v77
	s_waitcnt vmcnt(25)
	ds_write_b32 v38, v84
	s_waitcnt vmcnt(24)
	ds_write_b32 v40, v85
	s_waitcnt vmcnt(23)
	ds_write_b32 v42, v78
	s_waitcnt vmcnt(22)
	ds_write_b32 v58, v79
	s_waitcnt vmcnt(21)
	ds_write_b32 v60, v86
	s_waitcnt vmcnt(20)
	ds_write_b32 v62, v87
	s_waitcnt vmcnt(19)
	ds_write_b32 v64, v8
	s_waitcnt vmcnt(18)
	ds_write_b32 v66, v80
	s_waitcnt vmcnt(17)
	ds_write_b32 v68, v88
	s_waitcnt vmcnt(16)
	ds_write_b32 v70, v89
	s_waitcnt vmcnt(15)
	ds_write_b32 v126, v175
	s_waitcnt vmcnt(14)
	ds_write_b32 v128, v181
	s_waitcnt vmcnt(13)
	ds_write_b32 v130, v182
	s_waitcnt vmcnt(12)
	ds_write_b32 v132, v183
	s_waitcnt vmcnt(11)
	ds_write_b32 v134, v176
	s_waitcnt vmcnt(10)
	ds_write_b32 v136, v177
	s_waitcnt vmcnt(9)
	ds_write_b32 v138, v184
	s_waitcnt vmcnt(8)
	ds_write_b32 v140, v185
	s_waitcnt vmcnt(7)
	ds_write_b32 v142, v178
	s_waitcnt vmcnt(6)
	ds_write_b32 v158, v179
	s_waitcnt vmcnt(5)
	ds_write_b32 v160, v186
	s_waitcnt vmcnt(4)
	ds_write_b32 v162, v187
	s_waitcnt vmcnt(3)
	ds_write_b32 v164, v108
	s_waitcnt vmcnt(2)
	ds_write_b32 v166, v180
	s_waitcnt vmcnt(1)
	ds_write_b32 v168, v188
	s_waitcnt vmcnt(0)
	ds_write_b32 v170, v189
	s_cbranch_scc1 .LBB0_15
	s_waitcnt lgkmcnt(0)
	ds_read2_b32 v[28:29], v46 offset0:33 offset1:41
	ds_read2_b32 v[30:31], v46 offset1:8
	ds_read2_b32 v[32:33], v46 offset0:66 offset1:74
	ds_read2_b32 v[34:35], v46 offset0:99 offset1:107
	ds_read2_b32 v[36:37], v46 offset0:132 offset1:140
	ds_read2_b32 v[38:39], v46 offset0:165 offset1:173
	ds_read2_b32 v[40:41], v46 offset0:198 offset1:206
	ds_read2_b32 v[42:43], v46 offset0:231 offset1:239
	v_or_b32_e32 v5, s4, v45
	s_lshl_b32 s16, s5, 1
	v_mul_u32_u24_e32 v5, 0xb00, v5
	v_lshl_add_u64 v[58:59], v[10:11], 0, s[16:17]
	v_lshlrev_b32_e32 v8, 1, v5
	s_waitcnt lgkmcnt(6)
	v_cvt_pk_bf16_f32 v24, v30, v28
	s_waitcnt lgkmcnt(4)
	v_cvt_pk_bf16_f32 v25, v32, v34
	s_waitcnt lgkmcnt(2)
	v_cvt_pk_bf16_f32 v26, v36, v38
	s_waitcnt lgkmcnt(0)
	v_cvt_pk_bf16_f32 v27, v40, v42
	v_lshl_add_u64 v[60:61], v[58:59], 0, v[8:9]
	global_store_dwordx4 v[60:61], v[24:27], off
	v_or_b32_e32 v5, s4, v47
	v_mul_u32_u24_e32 v5, 0xb00, v5
	v_cvt_pk_bf16_f32 v24, v31, v29
	v_cvt_pk_bf16_f32 v25, v33, v35
	v_cvt_pk_bf16_f32 v26, v37, v39
	v_cvt_pk_bf16_f32 v27, v41, v43
	ds_read2_b32 v[30:31], v46 offset0:16 offset1:24
	ds_read2_b32 v[32:33], v46 offset0:49 offset1:57
	ds_read2_b32 v[34:35], v46 offset0:82 offset1:90
	ds_read2_b32 v[36:37], v46 offset0:115 offset1:123
	ds_read2_b32 v[38:39], v46 offset0:148 offset1:156
	ds_read2_b32 v[40:41], v46 offset0:181 offset1:189
	ds_read2_b32 v[42:43], v46 offset0:214 offset1:222
	ds_read2_b32 v[60:61], v46 offset0:247 offset1:255
	v_lshlrev_b32_e32 v8, 1, v5
	v_or_b32_e32 v5, s4, v48
	v_mul_u32_u24_e32 v5, 0xb00, v5
	v_lshl_add_u64 v[28:29], v[58:59], 0, v[8:9]
	v_lshlrev_b32_e32 v8, 1, v5
	v_or_b32_e32 v5, s4, v49
	v_mul_u32_u24_e32 v5, 0xb00, v5
	global_store_dwordx4 v[28:29], v[24:27], off
	v_lshl_add_u64 v[28:29], v[58:59], 0, v[8:9]
	v_lshlrev_b32_e32 v8, 1, v5
	s_waitcnt lgkmcnt(6)
	v_cvt_pk_bf16_f32 v24, v30, v32
	s_waitcnt lgkmcnt(4)
	v_cvt_pk_bf16_f32 v25, v34, v36
	s_waitcnt lgkmcnt(2)
	v_cvt_pk_bf16_f32 v26, v38, v40
	s_waitcnt lgkmcnt(0)
	v_cvt_pk_bf16_f32 v27, v42, v60
	global_store_dwordx4 v[28:29], v[24:27], off
	v_lshl_add_u64 v[28:29], v[58:59], 0, v[8:9]
	s_mov_b64 s[4:5], 0
	v_cvt_pk_bf16_f32 v24, v31, v33
	v_cvt_pk_bf16_f32 v25, v35, v37
	v_cvt_pk_bf16_f32 v26, v39, v41
	v_cvt_pk_bf16_f32 v27, v43, v61
	global_store_dwordx4 v[28:29], v[24:27], off
	s_waitcnt lgkmcnt(0)
.LBB0_17:
	s_and_b64 vcc, exec, s[4:5]
	s_cbranch_vccz .LBB0_38
	s_add_i32 s4, s40, 0xef00
	s_and_b32 s5, s4, 0xffff
	s_mul_i32 s16, s5, 0xba2f
	s_lshr_b32 s16, s16, 23
	s_mul_i32 s26, s16, 0xb0
	s_sub_i32 s4, s4, s26
	s_lshl_b32 s26, s4, 5
	s_bfe_i32 s27, s4, 0x10002
	s_lshl_b32 s4, s4, 4
	s_and_b32 s27, s27, 0xb00
	s_and_b32 s4, s4, 0xf80
	s_and_b32 s41, s26, 0xffe0
	s_and_b32 s26, s26, 0x60
	s_add_i32 s27, s27, s4
	s_or_b32 s4, s27, s26
	s_lshl_b32 s16, s16, 6
	v_or_b32_e32 v5, s4, v44
	v_lshlrev_b32_e32 v40, 2, v5
	v_or_b32_e32 v5, s16, v51
	v_mov_b32_e32 v41, v9
	v_mul_u32_u24_e32 v8, 0x5800, v5
	v_or_b32_e32 v5, s16, v52
	v_lshl_add_u64 v[24:25], v[40:41], 0, v[8:9]
	v_mul_u32_u24_e32 v8, 0x5800, v5
	v_or_b32_e32 v5, s16, v53
	v_lshl_add_u64 v[28:29], v[40:41], 0, v[8:9]
	v_mul_u32_u24_e32 v8, 0x5800, v5
	v_or_b32_e32 v5, s16, v54
	v_lshl_add_u64 v[30:31], v[40:41], 0, v[8:9]
	v_mul_u32_u24_e32 v8, 0x5800, v5
	v_or_b32_e32 v5, s16, v55
	v_lshl_add_u64 v[32:33], v[40:41], 0, v[8:9]
	v_mul_u32_u24_e32 v8, 0x5800, v5
	v_or_b32_e32 v5, s16, v56
	v_lshl_add_u64 v[34:35], v[40:41], 0, v[8:9]
	v_mul_u32_u24_e32 v8, 0x5800, v5
	v_or_b32_e32 v5, s16, v57
	s_mul_hi_u32 s4, s5, 0x1745d18
	v_lshl_add_u64 v[36:37], v[40:41], 0, v[8:9]
	v_mul_u32_u24_e32 v8, 0x5800, v5
	v_or_b32_e32 v5, s16, v4
	v_lshl_or_b32 v26, s4, 8, v22
	v_lshl_add_u64 v[38:39], v[40:41], 0, v[8:9]
	v_mad_u64_u32 v[40:41], s[4:5], v5, s37, v[40:41]
	v_lshl_add_u64 v[24:25], s[10:11], 0, v[24:25]
	v_mov_b32_e32 v27, v3
	v_lshl_add_u64 v[28:29], s[10:11], 0, v[28:29]
	v_lshl_add_u64 v[30:31], s[10:11], 0, v[30:31]
	v_lshl_add_u64 v[32:33], s[10:11], 0, v[32:33]
	v_lshl_add_u64 v[34:35], s[10:11], 0, v[34:35]
	v_lshl_add_u64 v[36:37], s[10:11], 0, v[36:37]
	v_lshl_add_u64 v[38:39], s[10:11], 0, v[38:39]
	v_lshlrev_b32_e32 v8, 2, v5
	v_lshl_add_u64 v[40:41], s[10:11], 0, v[40:41]
	s_mov_b64 s[26:27], 0
	s_mov_b64 s[28:29], s[8:9]
	v_mov_b32_e32 v5, v50
	s_and_b64 vcc, exec, s[22:23]
	s_cbranch_vccz .LBB0_21
	v_lshl_add_u64 v[42:43], s[28:29], 0, v[26:27]
	v_lshl_add_u64 v[58:59], s[28:29], 0, v[8:9]
	s_mov_b64 s[26:27], 0x0
	v_lshl_add_u64 v[60:61], v[40:41], 0, s[26:27]
	global_load_dword v100, v[60:61], off
	v_lshl_add_u64 v[60:61], v[38:39], 0, s[26:27]
	global_load_dword v101, v[60:61], off
	v_lshl_add_u64 v[60:61], v[36:37], 0, s[26:27]
	global_load_dword v102, v[60:61], off
	v_lshl_add_u64 v[60:61], v[34:35], 0, s[26:27]
	global_load_dword v103, v[60:61], off
	v_lshl_add_u64 v[60:61], v[32:33], 0, s[26:27]
	global_load_dword v104, v[60:61], off
	v_lshl_add_u64 v[60:61], v[30:31], 0, s[26:27]
	global_load_dword v105, v[60:61], off
	v_lshl_add_u64 v[60:61], v[28:29], 0, s[26:27]
	global_load_dword v106, v[60:61], off
	v_lshl_add_u64 v[60:61], v[24:25], 0, s[26:27]
	global_load_dword v107, v[60:61], off
	s_mov_b64 s[26:27], 0x58000
	v_lshl_add_u64 v[60:61], v[40:41], 0, s[26:27]
	global_load_dword v108, v[60:61], off
	v_lshl_add_u64 v[60:61], v[38:39], 0, s[26:27]
	global_load_dword v109, v[60:61], off
	v_lshl_add_u64 v[60:61], v[36:37], 0, s[26:27]
	global_load_dword v110, v[60:61], off
	v_lshl_add_u64 v[60:61], v[34:35], 0, s[26:27]
	global_load_dword v111, v[60:61], off
	v_lshl_add_u64 v[60:61], v[32:33], 0, s[26:27]
	global_load_dword v112, v[60:61], off
	v_lshl_add_u64 v[60:61], v[30:31], 0, s[26:27]
	global_load_dword v113, v[60:61], off
	v_lshl_add_u64 v[60:61], v[28:29], 0, s[26:27]
	global_load_dword v114, v[60:61], off
	v_lshl_add_u64 v[60:61], v[24:25], 0, s[26:27]
	global_load_dword v115, v[60:61], off
	s_mov_b64 s[26:27], 0xb0000
	v_lshl_add_u64 v[60:61], v[40:41], 0, s[26:27]
	global_load_dword v116, v[60:61], off
	v_lshl_add_u64 v[60:61], v[38:39], 0, s[26:27]
	global_load_dword v117, v[60:61], off
	v_lshl_add_u64 v[60:61], v[36:37], 0, s[26:27]
	global_load_dword v118, v[60:61], off
	v_lshl_add_u64 v[60:61], v[34:35], 0, s[26:27]
	global_load_dword v119, v[60:61], off
	v_lshl_add_u64 v[60:61], v[32:33], 0, s[26:27]
	global_load_dword v120, v[60:61], off
	v_lshl_add_u64 v[60:61], v[30:31], 0, s[26:27]
	global_load_dword v121, v[60:61], off
	v_lshl_add_u64 v[60:61], v[28:29], 0, s[26:27]
	global_load_dword v122, v[60:61], off
	v_lshl_add_u64 v[60:61], v[24:25], 0, s[26:27]
	global_load_dword v123, v[60:61], off
	s_mov_b64 s[26:27], 0x108000
	v_lshl_add_u64 v[60:61], v[40:41], 0, s[26:27]
	global_load_dword v124, v[60:61], off
	v_lshl_add_u64 v[60:61], v[38:39], 0, s[26:27]
	global_load_dword v125, v[60:61], off
	v_lshl_add_u64 v[60:61], v[36:37], 0, s[26:27]
	global_load_dword v126, v[60:61], off
	v_lshl_add_u64 v[60:61], v[34:35], 0, s[26:27]
	global_load_dword v127, v[60:61], off
	v_lshl_add_u64 v[60:61], v[32:33], 0, s[26:27]
	global_load_dword v128, v[60:61], off
	v_lshl_add_u64 v[60:61], v[30:31], 0, s[26:27]
	global_load_dword v129, v[60:61], off
	v_lshl_add_u64 v[60:61], v[28:29], 0, s[26:27]
	global_load_dword v130, v[60:61], off
	v_lshl_add_u64 v[60:61], v[24:25], 0, s[26:27]
	global_load_dword v131, v[60:61], off
	global_load_dword v132, v[58:59], off
	global_load_dword v133, v[42:43], off offset:8
	global_load_dword v134, v[42:43], off offset:16
	global_load_dword v135, v[42:43], off offset:24
	global_load_dword v136, v[42:43], off offset:32
	global_load_dword v137, v[42:43], off offset:40
	global_load_dword v138, v[42:43], off offset:48
	global_load_dword v139, v[42:43], off offset:56
	global_load_dword v140, v[58:59], off offset:64
	global_load_dword v141, v[42:43], off offset:72
	global_load_dword v142, v[42:43], off offset:80
	global_load_dword v143, v[42:43], off offset:88
	global_load_dword v144, v[42:43], off offset:96
	global_load_dword v145, v[42:43], off offset:104
	global_load_dword v146, v[42:43], off offset:112
	global_load_dword v147, v[42:43], off offset:120
	s_waitcnt vmcnt(15)
	global_load_dword v148, v[58:59], off offset:128
	global_load_dword v149, v[42:43], off offset:136
	global_load_dword v150, v[42:43], off offset:144
	global_load_dword v151, v[42:43], off offset:152
	global_load_dword v152, v[42:43], off offset:160
	global_load_dword v153, v[42:43], off offset:168
	global_load_dword v154, v[42:43], off offset:176
	global_load_dword v155, v[42:43], off offset:184
	global_load_dword v156, v[58:59], off offset:192
	global_load_dword v157, v[42:43], off offset:200
	global_load_dword v158, v[42:43], off offset:208
	global_load_dword v159, v[42:43], off offset:216
	global_load_dword v160, v[42:43], off offset:224
	global_load_dword v161, v[42:43], off offset:232
	global_load_dword v162, v[42:43], off offset:240
	global_load_dword v163, v[42:43], off offset:248
	v_mul_f32_e32 v100, v100, v132
	ds_write_b32 v50, v100
	s_waitcnt vmcnt(30)
	v_mul_f32_e32 v101, v101, v133
	ds_write_b32 v50, v101 offset:264
	s_waitcnt vmcnt(29)
	v_mul_f32_e32 v102, v102, v134
	ds_write_b32 v50, v102 offset:528
	s_waitcnt vmcnt(28)
	v_mul_f32_e32 v103, v103, v135
	ds_write_b32 v50, v103 offset:792
	s_waitcnt vmcnt(27)
	v_mul_f32_e32 v104, v104, v136
	ds_write_b32 v50, v104 offset:1056
	s_waitcnt vmcnt(26)
	v_mul_f32_e32 v105, v105, v137
	ds_write_b32 v50, v105 offset:1320
	s_waitcnt vmcnt(25)
	v_mul_f32_e32 v106, v106, v138
	ds_write_b32 v50, v106 offset:1584
	s_waitcnt vmcnt(24)
	v_mul_f32_e32 v107, v107, v139
	ds_write_b32 v50, v107 offset:1848
	s_waitcnt vmcnt(23)
	v_mul_f32_e32 v108, v108, v140
	ds_write_b32 v50, v108 offset:2112
	s_waitcnt vmcnt(22)
	v_mul_f32_e32 v109, v109, v141
	ds_write_b32 v50, v109 offset:2376
	s_waitcnt vmcnt(21)
	v_mul_f32_e32 v110, v110, v142
	ds_write_b32 v50, v110 offset:2640
	s_waitcnt vmcnt(20)
	v_mul_f32_e32 v111, v111, v143
	ds_write_b32 v50, v111 offset:2904
	s_waitcnt vmcnt(19)
	v_mul_f32_e32 v112, v112, v144
	ds_write_b32 v50, v112 offset:3168
	s_waitcnt vmcnt(18)
	v_mul_f32_e32 v113, v113, v145
	ds_write_b32 v50, v113 offset:3432
	s_waitcnt vmcnt(17)
	v_mul_f32_e32 v114, v114, v146
	ds_write_b32 v50, v114 offset:3696
	s_waitcnt vmcnt(16)
	v_mul_f32_e32 v115, v115, v147
	ds_write_b32 v50, v115 offset:3960
	s_waitcnt vmcnt(15)
	v_mul_f32_e32 v116, v116, v148
	ds_write_b32 v50, v116 offset:4224
	s_waitcnt vmcnt(14)
	v_mul_f32_e32 v117, v117, v149
	ds_write_b32 v50, v117 offset:4488
	s_waitcnt vmcnt(13)
	v_mul_f32_e32 v118, v118, v150
	ds_write_b32 v50, v118 offset:4752
	s_waitcnt vmcnt(12)
	v_mul_f32_e32 v119, v119, v151
	ds_write_b32 v50, v119 offset:5016
	s_waitcnt vmcnt(11)
	v_mul_f32_e32 v120, v120, v152
	ds_write_b32 v50, v120 offset:5280
	s_waitcnt vmcnt(10)
	v_mul_f32_e32 v121, v121, v153
	ds_write_b32 v50, v121 offset:5544
	s_waitcnt vmcnt(9)
	v_mul_f32_e32 v122, v122, v154
	ds_write_b32 v50, v122 offset:5808
	s_waitcnt vmcnt(8)
	v_mul_f32_e32 v123, v123, v155
	ds_write_b32 v50, v123 offset:6072
	s_waitcnt vmcnt(7)
	v_mul_f32_e32 v124, v124, v156
	ds_write_b32 v50, v124 offset:6336
	s_waitcnt vmcnt(6)
	v_mul_f32_e32 v125, v125, v157
	ds_write_b32 v50, v125 offset:6600
	s_waitcnt vmcnt(5)
	v_mul_f32_e32 v126, v126, v158
	ds_write_b32 v50, v126 offset:6864
	s_waitcnt vmcnt(4)
	v_mul_f32_e32 v127, v127, v159
	ds_write_b32 v50, v127 offset:7128
	s_waitcnt vmcnt(3)
	v_mul_f32_e32 v128, v128, v160
	ds_write_b32 v50, v128 offset:7392
	s_waitcnt vmcnt(2)
	v_mul_f32_e32 v129, v129, v161
	ds_write_b32 v50, v129 offset:7656
	s_waitcnt vmcnt(1)
	v_mul_f32_e32 v130, v130, v162
	ds_write_b32 v50, v130 offset:7920
	s_waitcnt vmcnt(0)
	v_mul_f32_e32 v131, v131, v163
	ds_write_b32 v50, v131 offset:8184
	s_branch .LBB0_37

.LBB0_41:
	s_lshl_b32 s29, s16, 1
	s_lshl_b32 s41, s27, 1
	v_or_b32_e32 v25, s29, v1
	v_or_b32_e32 v60, s41, v4
	s_add_i32 s43, s41, 4
	s_add_i32 s42, s29, 4
	s_add_i32 s44, s29, 8
	s_add_i32 s45, s41, 8
	s_add_i32 s46, s29, 12
	s_add_i32 s49, s29, 16
	s_add_i32 s51, s29, 20
	s_add_i32 s53, s29, 24
	s_add_i32 s29, s29, 28
	v_add_lshl_u32 v8, v25, s26, 10
	v_add_lshl_u32 v28, v60, s5, 10
	v_or_b32_e32 v62, s43, v4
	s_add_i32 s47, s41, 12
	v_or_b32_e32 v61, s42, v1
	v_or_b32_e32 v63, s44, v1
	v_or_b32_e32 v64, s45, v4
	v_or_b32_e32 v65, s46, v1
	v_or_b32_e32 v67, s49, v1
	v_or_b32_e32 v69, s51, v1
	v_or_b32_e32 v71, s53, v1
	v_or_b32_e32 v73, s29, v1
	v_or_b32_e32 v26, v5, v8
	v_or_b32_e32 v8, v24, v28
	v_add_lshl_u32 v30, v62, s5, 10
	v_mov_b32_e32 v27, v9
	s_add_i32 s50, s41, 16
	v_or_b32_e32 v66, s47, v4
	v_add_lshl_u32 v28, v61, s26, 10
	v_add_lshl_u32 v32, v63, s26, 10
	v_add_lshl_u32 v75, v64, s5, 10
	v_add_lshl_u32 v34, v65, s26, 10
	v_add_lshl_u32 v36, v67, s26, 10
	v_add_lshl_u32 v38, v69, s26, 10
	v_add_lshl_u32 v40, v71, s26, 10
	v_add_lshl_u32 v58, v73, s26, 10
	v_lshl_add_u64 v[42:43], v[8:9], 2, s[20:21]
	v_or_b32_e32 v8, v24, v30
	v_mov_b32_e32 v29, v9
	s_add_i32 s52, s41, 20
	v_or_b32_e32 v68, s50, v4
	v_add_lshl_u32 v76, v66, s5, 10
	v_lshl_add_u64 v[26:27], v[26:27], 2, s[20:21]
	v_or_b32_e32 v28, v5, v28
	v_or_b32_e32 v30, v5, v32
	v_or_b32_e32 v32, v5, v34
	v_or_b32_e32 v34, v5, v36
	v_or_b32_e32 v36, v5, v38
	v_or_b32_e32 v38, v5, v40
	v_or_b32_e32 v40, v5, v58
	v_lshl_add_u64 v[58:59], v[8:9], 2, s[20:21]
	v_or_b32_e32 v8, v24, v75
	s_add_i32 s54, s41, 24
	v_or_b32_e32 v70, s52, v4
	v_add_lshl_u32 v77, v68, s5, 10
	v_lshl_add_u64 v[28:29], v[28:29], 2, s[20:21]
	global_load_dword v75, v[42:43], off
	global_load_dword v81, v[26:27], off
	global_load_dword v82, v[58:59], off
	global_load_dword v83, v[28:29], off
	v_lshl_add_u64 v[26:27], v[8:9], 2, s[20:21]
	v_or_b32_e32 v8, v24, v76
	v_mov_b32_e32 v31, v9
	v_mov_b32_e32 v33, v9
	s_add_i32 s41, s41, 28
	v_or_b32_e32 v72, s54, v4
	v_add_lshl_u32 v78, v70, s5, 10
	v_lshl_add_u64 v[28:29], v[8:9], 2, s[20:21]
	v_or_b32_e32 v8, v24, v77
	v_or_b32_e32 v74, s41, v4
	v_add_lshl_u32 v79, v72, s5, 10
	v_lshl_add_u64 v[30:31], v[30:31], 2, s[20:21]
	v_lshl_add_u64 v[32:33], v[32:33], 2, s[20:21]
	global_load_dword v76, v[26:27], off
	global_load_dword v77, v[30:31], off
	global_load_dword v84, v[28:29], off
	global_load_dword v85, v[32:33], off
	v_lshl_add_u64 v[26:27], v[8:9], 2, s[20:21]
	v_or_b32_e32 v8, v24, v78
	v_mov_b32_e32 v35, v9
	v_mov_b32_e32 v37, v9
	v_add_lshl_u32 v80, v74, s5, 10
	v_lshl_add_u64 v[28:29], v[8:9], 2, s[20:21]
	v_or_b32_e32 v8, v24, v79
	v_mov_b32_e32 v39, v9
	v_mov_b32_e32 v41, v9
	v_lshl_add_u64 v[34:35], v[34:35], 2, s[20:21]
	v_lshl_add_u64 v[36:37], v[36:37], 2, s[20:21]
	global_load_dword v78, v[26:27], off
	global_load_dword v79, v[34:35], off
	global_load_dword v86, v[28:29], off
	global_load_dword v87, v[36:37], off
	v_lshl_add_u64 v[26:27], v[8:9], 2, s[20:21]
	v_or_b32_e32 v8, v24, v80
	v_lshl_add_u64 v[38:39], v[38:39], 2, s[20:21]
	v_lshl_add_u64 v[40:41], v[40:41], 2, s[20:21]
	v_lshl_add_u64 v[28:29], v[8:9], 2, s[20:21]
	global_load_dword v8, v[26:27], off
	global_load_dword v80, v[38:39], off
	global_load_dword v88, v[28:29], off
	global_load_dword v89, v[40:41], off
	s_add_i32 s27, s27, 16
	s_add_i32 s16, s16, 16
	s_add_i32 s28, s28, -16
	v_mad_u64_u32 v[26:27], s[42:43], v60, s36, v[6:7]
	s_cmp_lg_u32 s28, 0
	v_mad_u64_u32 v[28:29], s[42:43], v25, s36, v[6:7]
	v_mad_u64_u32 v[30:31], s[42:43], v62, s36, v[6:7]
	v_mad_u64_u32 v[32:33], s[42:43], v61, s36, v[6:7]
	v_mad_u64_u32 v[34:35], s[42:43], v64, s36, v[6:7]
	v_mad_u64_u32 v[36:37], s[42:43], v63, s36, v[6:7]
	v_mad_u64_u32 v[38:39], s[42:43], v66, s36, v[6:7]
	v_mad_u64_u32 v[40:41], s[42:43], v65, s36, v[6:7]
	v_mad_u64_u32 v[42:43], s[42:43], v68, s36, v[6:7]
	v_mad_u64_u32 v[58:59], s[42:43], v67, s36, v[6:7]
	v_mad_u64_u32 v[60:61], s[42:43], v70, s36, v[6:7]
	v_mad_u64_u32 v[62:63], s[42:43], v69, s36, v[6:7]
	v_mad_u64_u32 v[64:65], s[42:43], v72, s36, v[6:7]
	v_mad_u64_u32 v[66:67], s[42:43], v71, s36, v[6:7]
	v_mad_u64_u32 v[68:69], s[42:43], v74, s36, v[6:7]
	v_mad_u64_u32 v[70:71], s[42:43], v73, s36, v[6:7]
	v_mov_b32_e32 v109, v9
	s_lshl_b32 s29, s16, 1
	s_lshl_b32 s41, s27, 1
	v_or_b32_e32 v125, s29, v1
	v_or_b32_e32 v160, s41, v4
	s_add_i32 s43, s41, 4
	s_add_i32 s42, s29, 4
	s_add_i32 s44, s29, 8
	s_add_i32 s45, s41, 8
	s_add_i32 s46, s29, 12
	s_add_i32 s49, s29, 16
	s_add_i32 s51, s29, 20
	s_add_i32 s53, s29, 24
	s_add_i32 s29, s29, 28
	v_add_lshl_u32 v108, v125, s26, 10
	v_add_lshl_u32 v128, v160, s5, 10
	v_or_b32_e32 v162, s43, v4
	s_add_i32 s47, s41, 12
	v_or_b32_e32 v161, s42, v1
	v_or_b32_e32 v163, s44, v1
	v_or_b32_e32 v164, s45, v4
	v_or_b32_e32 v165, s46, v1
	v_or_b32_e32 v167, s49, v1
	v_or_b32_e32 v169, s51, v1
	v_or_b32_e32 v171, s53, v1
	v_or_b32_e32 v173, s29, v1
	v_or_b32_e32 v126, v5, v108
	v_or_b32_e32 v108, v24, v128
	v_add_lshl_u32 v130, v162, s5, 10
	v_mov_b32_e32 v127, v109
	s_add_i32 s50, s41, 16
	v_or_b32_e32 v166, s47, v4
	v_add_lshl_u32 v128, v161, s26, 10
	v_add_lshl_u32 v132, v163, s26, 10
	v_add_lshl_u32 v175, v164, s5, 10
	v_add_lshl_u32 v134, v165, s26, 10
	v_add_lshl_u32 v136, v167, s26, 10
	v_add_lshl_u32 v138, v169, s26, 10
	v_add_lshl_u32 v140, v171, s26, 10
	v_add_lshl_u32 v158, v173, s26, 10
	v_lshl_add_u64 v[142:143], v[108:109], 2, s[20:21]
	v_or_b32_e32 v108, v24, v130
	v_mov_b32_e32 v129, v109
	s_add_i32 s52, s41, 20
	v_or_b32_e32 v168, s50, v4
	v_add_lshl_u32 v176, v166, s5, 10
	v_lshl_add_u64 v[126:127], v[126:127], 2, s[20:21]
	v_or_b32_e32 v128, v5, v128
	v_or_b32_e32 v130, v5, v132
	v_or_b32_e32 v132, v5, v134
	v_or_b32_e32 v134, v5, v136
	v_or_b32_e32 v136, v5, v138
	v_or_b32_e32 v138, v5, v140
	v_or_b32_e32 v140, v5, v158
	v_lshl_add_u64 v[158:159], v[108:109], 2, s[20:21]
	v_or_b32_e32 v108, v24, v175
	s_add_i32 s54, s41, 24
	v_or_b32_e32 v170, s52, v4
	v_add_lshl_u32 v177, v168, s5, 10
	v_lshl_add_u64 v[128:129], v[128:129], 2, s[20:21]
	global_load_dword v175, v[142:143], off
	global_load_dword v181, v[126:127], off
	global_load_dword v182, v[158:159], off
	global_load_dword v183, v[128:129], off
	v_lshl_add_u64 v[126:127], v[108:109], 2, s[20:21]
	v_or_b32_e32 v108, v24, v176
	v_mov_b32_e32 v131, v109
	v_mov_b32_e32 v133, v109
	s_add_i32 s41, s41, 28
	v_or_b32_e32 v172, s54, v4
	v_add_lshl_u32 v178, v170, s5, 10
	v_lshl_add_u64 v[128:129], v[108:109], 2, s[20:21]
	v_or_b32_e32 v108, v24, v177
	v_or_b32_e32 v174, s41, v4
	v_add_lshl_u32 v179, v172, s5, 10
	v_lshl_add_u64 v[130:131], v[130:131], 2, s[20:21]
	v_lshl_add_u64 v[132:133], v[132:133], 2, s[20:21]
	global_load_dword v176, v[126:127], off
	global_load_dword v177, v[130:131], off
	global_load_dword v184, v[128:129], off
	global_load_dword v185, v[132:133], off
	v_lshl_add_u64 v[126:127], v[108:109], 2, s[20:21]
	v_or_b32_e32 v108, v24, v178
	v_mov_b32_e32 v135, v109
	v_mov_b32_e32 v137, v109
	v_add_lshl_u32 v180, v174, s5, 10
	v_lshl_add_u64 v[128:129], v[108:109], 2, s[20:21]
	v_or_b32_e32 v108, v24, v179
	v_mov_b32_e32 v139, v109
	v_mov_b32_e32 v141, v109
	v_lshl_add_u64 v[134:135], v[134:135], 2, s[20:21]
	v_lshl_add_u64 v[136:137], v[136:137], 2, s[20:21]
	global_load_dword v178, v[126:127], off
	global_load_dword v179, v[134:135], off
	global_load_dword v186, v[128:129], off
	global_load_dword v187, v[136:137], off
	v_lshl_add_u64 v[126:127], v[108:109], 2, s[20:21]
	v_or_b32_e32 v108, v24, v180
	v_lshl_add_u64 v[138:139], v[138:139], 2, s[20:21]
	v_lshl_add_u64 v[140:141], v[140:141], 2, s[20:21]
	v_lshl_add_u64 v[128:129], v[108:109], 2, s[20:21]
	global_load_dword v108, v[126:127], off
	global_load_dword v180, v[138:139], off
	global_load_dword v188, v[128:129], off
	global_load_dword v189, v[140:141], off
	s_add_i32 s27, s27, 16
	s_add_i32 s16, s16, 16
	s_add_i32 s28, s28, -16
	v_mad_u64_u32 v[126:127], s[42:43], v160, s36, v[6:7]
	s_cmp_lg_u32 s28, 0
	v_mad_u64_u32 v[128:129], s[42:43], v125, s36, v[6:7]
	v_mad_u64_u32 v[130:131], s[42:43], v162, s36, v[6:7]
	v_mad_u64_u32 v[132:133], s[42:43], v161, s36, v[6:7]
	v_mad_u64_u32 v[134:135], s[42:43], v164, s36, v[6:7]
	v_mad_u64_u32 v[136:137], s[42:43], v163, s36, v[6:7]
	v_mad_u64_u32 v[138:139], s[42:43], v166, s36, v[6:7]
	v_mad_u64_u32 v[140:141], s[42:43], v165, s36, v[6:7]
	v_mad_u64_u32 v[142:143], s[42:43], v168, s36, v[6:7]
	v_mad_u64_u32 v[158:159], s[42:43], v167, s36, v[6:7]
	v_mad_u64_u32 v[160:161], s[42:43], v170, s36, v[6:7]
	v_mad_u64_u32 v[162:163], s[42:43], v169, s36, v[6:7]
	v_mad_u64_u32 v[164:165], s[42:43], v172, s36, v[6:7]
	v_mad_u64_u32 v[166:167], s[42:43], v171, s36, v[6:7]
	v_mad_u64_u32 v[168:169], s[42:43], v174, s36, v[6:7]
	v_mad_u64_u32 v[170:171], s[42:43], v173, s36, v[6:7]
	s_waitcnt vmcnt(31)
	ds_write_b32 v26, v75
	s_waitcnt vmcnt(30)
	ds_write_b32 v28, v81
	s_waitcnt vmcnt(29)
	ds_write_b32 v30, v82
	s_waitcnt vmcnt(28)
	ds_write_b32 v32, v83
	s_waitcnt vmcnt(27)
	ds_write_b32 v34, v76
	s_waitcnt vmcnt(26)
	ds_write_b32 v36, v77
	s_waitcnt vmcnt(25)
	ds_write_b32 v38, v84
	s_waitcnt vmcnt(24)
	ds_write_b32 v40, v85
	s_waitcnt vmcnt(23)
	ds_write_b32 v42, v78
	s_waitcnt vmcnt(22)
	ds_write_b32 v58, v79
	s_waitcnt vmcnt(21)
	ds_write_b32 v60, v86
	s_waitcnt vmcnt(20)
	ds_write_b32 v62, v87
	s_waitcnt vmcnt(19)
	ds_write_b32 v64, v8
	s_waitcnt vmcnt(18)
	ds_write_b32 v66, v80
	s_waitcnt vmcnt(17)
	ds_write_b32 v68, v88
	s_waitcnt vmcnt(16)
	ds_write_b32 v70, v89
	s_waitcnt vmcnt(15)
	ds_write_b32 v126, v175
	s_waitcnt vmcnt(14)
	ds_write_b32 v128, v181
	s_waitcnt vmcnt(13)
	ds_write_b32 v130, v182
	s_waitcnt vmcnt(12)
	ds_write_b32 v132, v183
	s_waitcnt vmcnt(11)
	ds_write_b32 v134, v176
	s_waitcnt vmcnt(10)
	ds_write_b32 v136, v177
	s_waitcnt vmcnt(9)
	ds_write_b32 v138, v184
	s_waitcnt vmcnt(8)
	ds_write_b32 v140, v185
	s_waitcnt vmcnt(7)
	ds_write_b32 v142, v178
	s_waitcnt vmcnt(6)
	ds_write_b32 v158, v179
	s_waitcnt vmcnt(5)
	ds_write_b32 v160, v186
	s_waitcnt vmcnt(4)
	ds_write_b32 v162, v187
	s_waitcnt vmcnt(3)
	ds_write_b32 v164, v108
	s_waitcnt vmcnt(2)
	ds_write_b32 v166, v180
	s_waitcnt vmcnt(1)
	ds_write_b32 v168, v188
	s_waitcnt vmcnt(0)
	ds_write_b32 v170, v189
	s_cbranch_scc1 .LBB0_41
	s_waitcnt lgkmcnt(0)
	ds_read2_b32 v[28:29], v46 offset0:33 offset1:41
	ds_read2_b32 v[30:31], v46 offset1:8
	ds_read2_b32 v[32:33], v46 offset0:66 offset1:74
	ds_read2_b32 v[34:35], v46 offset0:99 offset1:107
	ds_read2_b32 v[36:37], v46 offset0:132 offset1:140
	ds_read2_b32 v[38:39], v46 offset0:165 offset1:173
	ds_read2_b32 v[40:41], v46 offset0:198 offset1:206
	ds_read2_b32 v[42:43], v46 offset0:231 offset1:239
	s_lshl_b32 s16, s5, 1
	v_or_b32_e32 v5, s4, v45
	v_lshl_add_u64 v[58:59], v[14:15], 0, s[16:17]
	v_lshlrev_b32_e32 v8, 11, v5
	s_waitcnt lgkmcnt(6)
	v_cvt_pk_bf16_f32 v24, v30, v28
	s_waitcnt lgkmcnt(4)
	v_cvt_pk_bf16_f32 v25, v32, v34
	s_waitcnt lgkmcnt(2)
	v_cvt_pk_bf16_f32 v26, v36, v38
	s_waitcnt lgkmcnt(0)
	v_cvt_pk_bf16_f32 v27, v40, v42
	v_lshl_add_u64 v[60:61], v[58:59], 0, v[8:9]
	global_store_dwordx4 v[60:61], v[24:27], off
	v_or_b32_e32 v5, s4, v47
	v_lshlrev_b32_e32 v8, 11, v5
	v_cvt_pk_bf16_f32 v24, v31, v29
	v_cvt_pk_bf16_f32 v25, v33, v35
	v_cvt_pk_bf16_f32 v26, v37, v39
	v_cvt_pk_bf16_f32 v27, v41, v43
	ds_read2_b32 v[30:31], v46 offset0:49 offset1:57
	ds_read2_b32 v[32:33], v46 offset0:16 offset1:24
	ds_read2_b32 v[34:35], v46 offset0:82 offset1:90
	ds_read2_b32 v[36:37], v46 offset0:115 offset1:123
	ds_read2_b32 v[38:39], v46 offset0:148 offset1:156
	ds_read2_b32 v[40:41], v46 offset0:181 offset1:189
	ds_read2_b32 v[42:43], v46 offset0:214 offset1:222
	ds_read2_b32 v[60:61], v46 offset0:247 offset1:255
	v_or_b32_e32 v5, s4, v48
	v_lshl_add_u64 v[28:29], v[58:59], 0, v[8:9]
	v_lshlrev_b32_e32 v8, 11, v5
	v_or_b32_e32 v5, s4, v49
	global_store_dwordx4 v[28:29], v[24:27], off
	v_lshl_add_u64 v[28:29], v[58:59], 0, v[8:9]
	v_lshlrev_b32_e32 v8, 11, v5
	s_waitcnt lgkmcnt(6)
	v_cvt_pk_bf16_f32 v24, v32, v30
	s_waitcnt lgkmcnt(4)
	v_cvt_pk_bf16_f32 v25, v34, v36
	s_waitcnt lgkmcnt(2)
	v_cvt_pk_bf16_f32 v26, v38, v40
	s_waitcnt lgkmcnt(0)
	v_cvt_pk_bf16_f32 v27, v42, v60
	global_store_dwordx4 v[28:29], v[24:27], off
	v_lshl_add_u64 v[28:29], v[58:59], 0, v[8:9]
	s_nop 0
	v_cvt_pk_bf16_f32 v24, v33, v31
	v_cvt_pk_bf16_f32 v25, v35, v37
	v_cvt_pk_bf16_f32 v26, v39, v41
	v_cvt_pk_bf16_f32 v27, v43, v61
	global_store_dwordx4 v[28:29], v[24:27], off
	s_waitcnt lgkmcnt(0)

.LBB0_46:
	s_lshl_b32 s29, s16, 1
	s_lshl_b32 s41, s27, 1
	v_or_b32_e32 v25, s29, v1
	v_or_b32_e32 v60, s41, v4
	s_add_i32 s43, s41, 4
	s_add_i32 s42, s29, 4
	s_add_i32 s44, s29, 8
	s_add_i32 s45, s41, 8
	s_add_i32 s46, s29, 12
	s_add_i32 s49, s29, 16
	s_add_i32 s51, s29, 20
	s_add_i32 s53, s29, 24
	s_add_i32 s29, s29, 28
	v_add_lshl_u32 v8, v25, s26, 10
	v_add_lshl_u32 v28, v60, s5, 10
	v_or_b32_e32 v62, s43, v4
	s_add_i32 s47, s41, 12
	v_or_b32_e32 v61, s42, v1
	v_or_b32_e32 v63, s44, v1
	v_or_b32_e32 v64, s45, v4
	v_or_b32_e32 v65, s46, v1
	v_or_b32_e32 v67, s49, v1
	v_or_b32_e32 v69, s51, v1
	v_or_b32_e32 v71, s53, v1
	v_or_b32_e32 v73, s29, v1
	v_or_b32_e32 v26, v5, v8
	v_or_b32_e32 v8, v24, v28
	v_add_lshl_u32 v30, v62, s5, 10
	v_mov_b32_e32 v27, v9
	s_add_i32 s50, s41, 16
	v_or_b32_e32 v66, s47, v4
	v_add_lshl_u32 v28, v61, s26, 10
	v_add_lshl_u32 v32, v63, s26, 10
	v_add_lshl_u32 v75, v64, s5, 10
	v_add_lshl_u32 v34, v65, s26, 10
	v_add_lshl_u32 v36, v67, s26, 10
	v_add_lshl_u32 v38, v69, s26, 10
	v_add_lshl_u32 v40, v71, s26, 10
	v_add_lshl_u32 v58, v73, s26, 10
	v_lshl_add_u64 v[42:43], v[8:9], 2, s[14:15]
	v_or_b32_e32 v8, v24, v30
	v_mov_b32_e32 v29, v9
	s_add_i32 s52, s41, 20
	v_or_b32_e32 v68, s50, v4
	v_add_lshl_u32 v76, v66, s5, 10
	v_lshl_add_u64 v[26:27], v[26:27], 2, s[14:15]
	v_or_b32_e32 v28, v5, v28
	v_or_b32_e32 v30, v5, v32
	v_or_b32_e32 v32, v5, v34
	v_or_b32_e32 v34, v5, v36
	v_or_b32_e32 v36, v5, v38
	v_or_b32_e32 v38, v5, v40
	v_or_b32_e32 v40, v5, v58
	v_lshl_add_u64 v[58:59], v[8:9], 2, s[14:15]
	v_or_b32_e32 v8, v24, v75
	s_add_i32 s54, s41, 24
	v_or_b32_e32 v70, s52, v4
	v_add_lshl_u32 v77, v68, s5, 10
	v_lshl_add_u64 v[28:29], v[28:29], 2, s[14:15]
	global_load_dword v75, v[42:43], off
	global_load_dword v81, v[26:27], off
	global_load_dword v82, v[58:59], off
	global_load_dword v83, v[28:29], off
	v_lshl_add_u64 v[26:27], v[8:9], 2, s[14:15]
	v_or_b32_e32 v8, v24, v76
	v_mov_b32_e32 v31, v9
	v_mov_b32_e32 v33, v9
	s_add_i32 s41, s41, 28
	v_or_b32_e32 v72, s54, v4
	v_add_lshl_u32 v78, v70, s5, 10
	v_lshl_add_u64 v[28:29], v[8:9], 2, s[14:15]
	v_or_b32_e32 v8, v24, v77
	v_or_b32_e32 v74, s41, v4
	v_add_lshl_u32 v79, v72, s5, 10
	v_lshl_add_u64 v[30:31], v[30:31], 2, s[14:15]
	v_lshl_add_u64 v[32:33], v[32:33], 2, s[14:15]
	global_load_dword v76, v[26:27], off
	global_load_dword v77, v[30:31], off
	global_load_dword v84, v[28:29], off
	global_load_dword v85, v[32:33], off
	v_lshl_add_u64 v[26:27], v[8:9], 2, s[14:15]
	v_or_b32_e32 v8, v24, v78
	v_mov_b32_e32 v35, v9
	v_mov_b32_e32 v37, v9
	v_add_lshl_u32 v80, v74, s5, 10
	v_lshl_add_u64 v[28:29], v[8:9], 2, s[14:15]
	v_or_b32_e32 v8, v24, v79
	v_mov_b32_e32 v39, v9
	v_mov_b32_e32 v41, v9
	v_lshl_add_u64 v[34:35], v[34:35], 2, s[14:15]
	v_lshl_add_u64 v[36:37], v[36:37], 2, s[14:15]
	global_load_dword v78, v[26:27], off
	global_load_dword v79, v[34:35], off
	global_load_dword v86, v[28:29], off
	global_load_dword v87, v[36:37], off
	v_lshl_add_u64 v[26:27], v[8:9], 2, s[14:15]
	v_or_b32_e32 v8, v24, v80
	v_lshl_add_u64 v[38:39], v[38:39], 2, s[14:15]
	v_lshl_add_u64 v[40:41], v[40:41], 2, s[14:15]
	v_lshl_add_u64 v[28:29], v[8:9], 2, s[14:15]
	global_load_dword v8, v[26:27], off
	global_load_dword v80, v[38:39], off
	global_load_dword v88, v[28:29], off
	global_load_dword v89, v[40:41], off
	s_add_i32 s27, s27, 16
	s_add_i32 s16, s16, 16
	s_add_i32 s28, s28, -16
	v_mad_u64_u32 v[26:27], s[42:43], v60, s36, v[6:7]
	s_cmp_lg_u32 s28, 0
	v_mad_u64_u32 v[28:29], s[42:43], v25, s36, v[6:7]
	v_mad_u64_u32 v[30:31], s[42:43], v62, s36, v[6:7]
	v_mad_u64_u32 v[32:33], s[42:43], v61, s36, v[6:7]
	v_mad_u64_u32 v[34:35], s[42:43], v64, s36, v[6:7]
	v_mad_u64_u32 v[36:37], s[42:43], v63, s36, v[6:7]
	v_mad_u64_u32 v[38:39], s[42:43], v66, s36, v[6:7]
	v_mad_u64_u32 v[40:41], s[42:43], v65, s36, v[6:7]
	v_mad_u64_u32 v[42:43], s[42:43], v68, s36, v[6:7]
	v_mad_u64_u32 v[58:59], s[42:43], v67, s36, v[6:7]
	v_mad_u64_u32 v[60:61], s[42:43], v70, s36, v[6:7]
	v_mad_u64_u32 v[62:63], s[42:43], v69, s36, v[6:7]
	v_mad_u64_u32 v[64:65], s[42:43], v72, s36, v[6:7]
	v_mad_u64_u32 v[66:67], s[42:43], v71, s36, v[6:7]
	v_mad_u64_u32 v[68:69], s[42:43], v74, s36, v[6:7]
	v_mad_u64_u32 v[70:71], s[42:43], v73, s36, v[6:7]
	v_mov_b32_e32 v109, v9
	s_lshl_b32 s29, s16, 1
	s_lshl_b32 s41, s27, 1
	v_or_b32_e32 v125, s29, v1
	v_or_b32_e32 v160, s41, v4
	s_add_i32 s43, s41, 4
	s_add_i32 s42, s29, 4
	s_add_i32 s44, s29, 8
	s_add_i32 s45, s41, 8
	s_add_i32 s46, s29, 12
	s_add_i32 s49, s29, 16
	s_add_i32 s51, s29, 20
	s_add_i32 s53, s29, 24
	s_add_i32 s29, s29, 28
	v_add_lshl_u32 v108, v125, s26, 10
	v_add_lshl_u32 v128, v160, s5, 10
	v_or_b32_e32 v162, s43, v4
	s_add_i32 s47, s41, 12
	v_or_b32_e32 v161, s42, v1
	v_or_b32_e32 v163, s44, v1
	v_or_b32_e32 v164, s45, v4
	v_or_b32_e32 v165, s46, v1
	v_or_b32_e32 v167, s49, v1
	v_or_b32_e32 v169, s51, v1
	v_or_b32_e32 v171, s53, v1
	v_or_b32_e32 v173, s29, v1
	v_or_b32_e32 v126, v5, v108
	v_or_b32_e32 v108, v24, v128
	v_add_lshl_u32 v130, v162, s5, 10
	v_mov_b32_e32 v127, v109
	s_add_i32 s50, s41, 16
	v_or_b32_e32 v166, s47, v4
	v_add_lshl_u32 v128, v161, s26, 10
	v_add_lshl_u32 v132, v163, s26, 10
	v_add_lshl_u32 v175, v164, s5, 10
	v_add_lshl_u32 v134, v165, s26, 10
	v_add_lshl_u32 v136, v167, s26, 10
	v_add_lshl_u32 v138, v169, s26, 10
	v_add_lshl_u32 v140, v171, s26, 10
	v_add_lshl_u32 v158, v173, s26, 10
	v_lshl_add_u64 v[142:143], v[108:109], 2, s[14:15]
	v_or_b32_e32 v108, v24, v130
	v_mov_b32_e32 v129, v109
	s_add_i32 s52, s41, 20
	v_or_b32_e32 v168, s50, v4
	v_add_lshl_u32 v176, v166, s5, 10
	v_lshl_add_u64 v[126:127], v[126:127], 2, s[14:15]
	v_or_b32_e32 v128, v5, v128
	v_or_b32_e32 v130, v5, v132
	v_or_b32_e32 v132, v5, v134
	v_or_b32_e32 v134, v5, v136
	v_or_b32_e32 v136, v5, v138
	v_or_b32_e32 v138, v5, v140
	v_or_b32_e32 v140, v5, v158
	v_lshl_add_u64 v[158:159], v[108:109], 2, s[14:15]
	v_or_b32_e32 v108, v24, v175
	s_add_i32 s54, s41, 24
	v_or_b32_e32 v170, s52, v4
	v_add_lshl_u32 v177, v168, s5, 10
	v_lshl_add_u64 v[128:129], v[128:129], 2, s[14:15]
	global_load_dword v175, v[142:143], off
	global_load_dword v181, v[126:127], off
	global_load_dword v182, v[158:159], off
	global_load_dword v183, v[128:129], off
	v_lshl_add_u64 v[126:127], v[108:109], 2, s[14:15]
	v_or_b32_e32 v108, v24, v176
	v_mov_b32_e32 v131, v109
	v_mov_b32_e32 v133, v109
	s_add_i32 s41, s41, 28
	v_or_b32_e32 v172, s54, v4
	v_add_lshl_u32 v178, v170, s5, 10
	v_lshl_add_u64 v[128:129], v[108:109], 2, s[14:15]
	v_or_b32_e32 v108, v24, v177
	v_or_b32_e32 v174, s41, v4
	v_add_lshl_u32 v179, v172, s5, 10
	v_lshl_add_u64 v[130:131], v[130:131], 2, s[14:15]
	v_lshl_add_u64 v[132:133], v[132:133], 2, s[14:15]
	global_load_dword v176, v[126:127], off
	global_load_dword v177, v[130:131], off
	global_load_dword v184, v[128:129], off
	global_load_dword v185, v[132:133], off
	v_lshl_add_u64 v[126:127], v[108:109], 2, s[14:15]
	v_or_b32_e32 v108, v24, v178
	v_mov_b32_e32 v135, v109
	v_mov_b32_e32 v137, v109
	v_add_lshl_u32 v180, v174, s5, 10
	v_lshl_add_u64 v[128:129], v[108:109], 2, s[14:15]
	v_or_b32_e32 v108, v24, v179
	v_mov_b32_e32 v139, v109
	v_mov_b32_e32 v141, v109
	v_lshl_add_u64 v[134:135], v[134:135], 2, s[14:15]
	v_lshl_add_u64 v[136:137], v[136:137], 2, s[14:15]
	global_load_dword v178, v[126:127], off
	global_load_dword v179, v[134:135], off
	global_load_dword v186, v[128:129], off
	global_load_dword v187, v[136:137], off
	v_lshl_add_u64 v[126:127], v[108:109], 2, s[14:15]
	v_or_b32_e32 v108, v24, v180
	v_lshl_add_u64 v[138:139], v[138:139], 2, s[14:15]
	v_lshl_add_u64 v[140:141], v[140:141], 2, s[14:15]
	v_lshl_add_u64 v[128:129], v[108:109], 2, s[14:15]
	global_load_dword v108, v[126:127], off
	global_load_dword v180, v[138:139], off
	global_load_dword v188, v[128:129], off
	global_load_dword v189, v[140:141], off
	s_add_i32 s27, s27, 16
	s_add_i32 s16, s16, 16
	s_add_i32 s28, s28, -16
	v_mad_u64_u32 v[126:127], s[42:43], v160, s36, v[6:7]
	s_cmp_lg_u32 s28, 0
	v_mad_u64_u32 v[128:129], s[42:43], v125, s36, v[6:7]
	v_mad_u64_u32 v[130:131], s[42:43], v162, s36, v[6:7]
	v_mad_u64_u32 v[132:133], s[42:43], v161, s36, v[6:7]
	v_mad_u64_u32 v[134:135], s[42:43], v164, s36, v[6:7]
	v_mad_u64_u32 v[136:137], s[42:43], v163, s36, v[6:7]
	v_mad_u64_u32 v[138:139], s[42:43], v166, s36, v[6:7]
	v_mad_u64_u32 v[140:141], s[42:43], v165, s36, v[6:7]
	v_mad_u64_u32 v[142:143], s[42:43], v168, s36, v[6:7]
	v_mad_u64_u32 v[158:159], s[42:43], v167, s36, v[6:7]
	v_mad_u64_u32 v[160:161], s[42:43], v170, s36, v[6:7]
	v_mad_u64_u32 v[162:163], s[42:43], v169, s36, v[6:7]
	v_mad_u64_u32 v[164:165], s[42:43], v172, s36, v[6:7]
	v_mad_u64_u32 v[166:167], s[42:43], v171, s36, v[6:7]
	v_mad_u64_u32 v[168:169], s[42:43], v174, s36, v[6:7]
	v_mad_u64_u32 v[170:171], s[42:43], v173, s36, v[6:7]
	s_waitcnt vmcnt(31)
	ds_write_b32 v26, v75
	s_waitcnt vmcnt(30)
	ds_write_b32 v28, v81
	s_waitcnt vmcnt(29)
	ds_write_b32 v30, v82
	s_waitcnt vmcnt(28)
	ds_write_b32 v32, v83
	s_waitcnt vmcnt(27)
	ds_write_b32 v34, v76
	s_waitcnt vmcnt(26)
	ds_write_b32 v36, v77
	s_waitcnt vmcnt(25)
	ds_write_b32 v38, v84
	s_waitcnt vmcnt(24)
	ds_write_b32 v40, v85
	s_waitcnt vmcnt(23)
	ds_write_b32 v42, v78
	s_waitcnt vmcnt(22)
	ds_write_b32 v58, v79
	s_waitcnt vmcnt(21)
	ds_write_b32 v60, v86
	s_waitcnt vmcnt(20)
	ds_write_b32 v62, v87
	s_waitcnt vmcnt(19)
	ds_write_b32 v64, v8
	s_waitcnt vmcnt(18)
	ds_write_b32 v66, v80
	s_waitcnt vmcnt(17)
	ds_write_b32 v68, v88
	s_waitcnt vmcnt(16)
	ds_write_b32 v70, v89
	s_waitcnt vmcnt(15)
	ds_write_b32 v126, v175
	s_waitcnt vmcnt(14)
	ds_write_b32 v128, v181
	s_waitcnt vmcnt(13)
	ds_write_b32 v130, v182
	s_waitcnt vmcnt(12)
	ds_write_b32 v132, v183
	s_waitcnt vmcnt(11)
	ds_write_b32 v134, v176
	s_waitcnt vmcnt(10)
	ds_write_b32 v136, v177
	s_waitcnt vmcnt(9)
	ds_write_b32 v138, v184
	s_waitcnt vmcnt(8)
	ds_write_b32 v140, v185
	s_waitcnt vmcnt(7)
	ds_write_b32 v142, v178
	s_waitcnt vmcnt(6)
	ds_write_b32 v158, v179
	s_waitcnt vmcnt(5)
	ds_write_b32 v160, v186
	s_waitcnt vmcnt(4)
	ds_write_b32 v162, v187
	s_waitcnt vmcnt(3)
	ds_write_b32 v164, v108
	s_waitcnt vmcnt(2)
	ds_write_b32 v166, v180
	s_waitcnt vmcnt(1)
	ds_write_b32 v168, v188
	s_waitcnt vmcnt(0)
	ds_write_b32 v170, v189
	s_cbranch_scc1 .LBB0_46
	s_waitcnt lgkmcnt(0)
	ds_read2_b32 v[28:29], v46 offset0:33 offset1:41
	ds_read2_b32 v[30:31], v46 offset1:8
	ds_read2_b32 v[32:33], v46 offset0:66 offset1:74
	ds_read2_b32 v[34:35], v46 offset0:99 offset1:107
	ds_read2_b32 v[36:37], v46 offset0:132 offset1:140
	ds_read2_b32 v[38:39], v46 offset0:165 offset1:173
	ds_read2_b32 v[40:41], v46 offset0:198 offset1:206
	ds_read2_b32 v[42:43], v46 offset0:231 offset1:239
	s_lshl_b32 s16, s5, 1
	v_or_b32_e32 v5, s4, v45
	v_lshl_add_u64 v[58:59], v[16:17], 0, s[16:17]
	v_lshlrev_b32_e32 v8, 11, v5
	s_waitcnt lgkmcnt(6)
	v_cvt_pk_bf16_f32 v24, v30, v28
	s_waitcnt lgkmcnt(4)
	v_cvt_pk_bf16_f32 v25, v32, v34
	s_waitcnt lgkmcnt(2)
	v_cvt_pk_bf16_f32 v26, v36, v38
	s_waitcnt lgkmcnt(0)
	v_cvt_pk_bf16_f32 v27, v40, v42
	v_lshl_add_u64 v[60:61], v[58:59], 0, v[8:9]
	global_store_dwordx4 v[60:61], v[24:27], off
	v_or_b32_e32 v5, s4, v47
	v_lshlrev_b32_e32 v8, 11, v5
	v_cvt_pk_bf16_f32 v24, v31, v29
	v_cvt_pk_bf16_f32 v25, v33, v35
	v_cvt_pk_bf16_f32 v26, v37, v39
	v_cvt_pk_bf16_f32 v27, v41, v43
	ds_read2_b32 v[30:31], v46 offset0:49 offset1:57
	ds_read2_b32 v[32:33], v46 offset0:16 offset1:24
	ds_read2_b32 v[34:35], v46 offset0:82 offset1:90
	ds_read2_b32 v[36:37], v46 offset0:115 offset1:123
	ds_read2_b32 v[38:39], v46 offset0:148 offset1:156
	ds_read2_b32 v[40:41], v46 offset0:181 offset1:189
	ds_read2_b32 v[42:43], v46 offset0:214 offset1:222
	ds_read2_b32 v[60:61], v46 offset0:247 offset1:255
	v_or_b32_e32 v5, s4, v48
	v_lshl_add_u64 v[28:29], v[58:59], 0, v[8:9]
	v_lshlrev_b32_e32 v8, 11, v5
	v_or_b32_e32 v5, s4, v49
	global_store_dwordx4 v[28:29], v[24:27], off
	v_lshl_add_u64 v[28:29], v[58:59], 0, v[8:9]
	v_lshlrev_b32_e32 v8, 11, v5
	s_waitcnt lgkmcnt(6)
	v_cvt_pk_bf16_f32 v24, v32, v30
	s_waitcnt lgkmcnt(4)
	v_cvt_pk_bf16_f32 v25, v34, v36
	s_waitcnt lgkmcnt(2)
	v_cvt_pk_bf16_f32 v26, v38, v40
	s_waitcnt lgkmcnt(0)
	v_cvt_pk_bf16_f32 v27, v42, v60
	global_store_dwordx4 v[28:29], v[24:27], off
	v_lshl_add_u64 v[28:29], v[58:59], 0, v[8:9]
	s_nop 0
	v_cvt_pk_bf16_f32 v24, v33, v31
	v_cvt_pk_bf16_f32 v25, v35, v37
	v_cvt_pk_bf16_f32 v26, v39, v41
	v_cvt_pk_bf16_f32 v27, v43, v61
	global_store_dwordx4 v[28:29], v[24:27], off
	s_waitcnt lgkmcnt(0)

.LBB0_51:
	s_lshl_b32 s29, s16, 1
	s_lshl_b32 s41, s27, 1
	v_or_b32_e32 v25, s29, v1
	v_or_b32_e32 v60, s41, v4
	s_add_i32 s43, s41, 4
	s_add_i32 s42, s29, 4
	s_add_i32 s44, s29, 8
	s_add_i32 s45, s41, 8
	s_add_i32 s46, s29, 12
	s_add_i32 s49, s29, 16
	s_add_i32 s51, s29, 20
	s_add_i32 s53, s29, 24
	s_add_i32 s29, s29, 28
	v_add_lshl_u32 v8, v25, s26, 10
	v_add_lshl_u32 v28, v60, s5, 10
	v_or_b32_e32 v62, s43, v4
	s_add_i32 s47, s41, 12
	v_or_b32_e32 v61, s42, v1
	v_or_b32_e32 v63, s44, v1
	v_or_b32_e32 v64, s45, v4
	v_or_b32_e32 v65, s46, v1
	v_or_b32_e32 v67, s49, v1
	v_or_b32_e32 v69, s51, v1
	v_or_b32_e32 v71, s53, v1
	v_or_b32_e32 v73, s29, v1
	v_or_b32_e32 v26, v5, v8
	v_or_b32_e32 v8, v24, v28
	v_add_lshl_u32 v30, v62, s5, 10
	v_mov_b32_e32 v27, v9
	s_add_i32 s50, s41, 16
	v_or_b32_e32 v66, s47, v4
	v_add_lshl_u32 v28, v61, s26, 10
	v_add_lshl_u32 v32, v63, s26, 10
	v_add_lshl_u32 v75, v64, s5, 10
	v_add_lshl_u32 v34, v65, s26, 10
	v_add_lshl_u32 v36, v67, s26, 10
	v_add_lshl_u32 v38, v69, s26, 10
	v_add_lshl_u32 v40, v71, s26, 10
	v_add_lshl_u32 v58, v73, s26, 10
	v_lshl_add_u64 v[42:43], v[8:9], 2, s[12:13]
	v_or_b32_e32 v8, v24, v30
	v_mov_b32_e32 v29, v9
	s_add_i32 s52, s41, 20
	v_or_b32_e32 v68, s50, v4
	v_add_lshl_u32 v76, v66, s5, 10
	v_lshl_add_u64 v[26:27], v[26:27], 2, s[12:13]
	v_or_b32_e32 v28, v5, v28
	v_or_b32_e32 v30, v5, v32
	v_or_b32_e32 v32, v5, v34
	v_or_b32_e32 v34, v5, v36
	v_or_b32_e32 v36, v5, v38
	v_or_b32_e32 v38, v5, v40
	v_or_b32_e32 v40, v5, v58
	v_lshl_add_u64 v[58:59], v[8:9], 2, s[12:13]
	v_or_b32_e32 v8, v24, v75
	s_add_i32 s54, s41, 24
	v_or_b32_e32 v70, s52, v4
	v_add_lshl_u32 v77, v68, s5, 10
	v_lshl_add_u64 v[28:29], v[28:29], 2, s[12:13]
	global_load_dword v75, v[42:43], off
	global_load_dword v81, v[26:27], off
	global_load_dword v82, v[58:59], off
	global_load_dword v83, v[28:29], off
	v_lshl_add_u64 v[26:27], v[8:9], 2, s[12:13]
	v_or_b32_e32 v8, v24, v76
	v_mov_b32_e32 v31, v9
	v_mov_b32_e32 v33, v9
	s_add_i32 s41, s41, 28
	v_or_b32_e32 v72, s54, v4
	v_add_lshl_u32 v78, v70, s5, 10
	v_lshl_add_u64 v[28:29], v[8:9], 2, s[12:13]
	v_or_b32_e32 v8, v24, v77
	v_or_b32_e32 v74, s41, v4
	v_add_lshl_u32 v79, v72, s5, 10
	v_lshl_add_u64 v[30:31], v[30:31], 2, s[12:13]
	v_lshl_add_u64 v[32:33], v[32:33], 2, s[12:13]
	global_load_dword v76, v[26:27], off
	global_load_dword v77, v[30:31], off
	global_load_dword v84, v[28:29], off
	global_load_dword v85, v[32:33], off
	v_lshl_add_u64 v[26:27], v[8:9], 2, s[12:13]
	v_or_b32_e32 v8, v24, v78
	v_mov_b32_e32 v35, v9
	v_mov_b32_e32 v37, v9
	v_add_lshl_u32 v80, v74, s5, 10
	v_lshl_add_u64 v[28:29], v[8:9], 2, s[12:13]
	v_or_b32_e32 v8, v24, v79
	v_mov_b32_e32 v39, v9
	v_mov_b32_e32 v41, v9
	v_lshl_add_u64 v[34:35], v[34:35], 2, s[12:13]
	v_lshl_add_u64 v[36:37], v[36:37], 2, s[12:13]
	global_load_dword v78, v[26:27], off
	global_load_dword v79, v[34:35], off
	global_load_dword v86, v[28:29], off
	global_load_dword v87, v[36:37], off
	v_lshl_add_u64 v[26:27], v[8:9], 2, s[12:13]
	v_or_b32_e32 v8, v24, v80
	v_lshl_add_u64 v[38:39], v[38:39], 2, s[12:13]
	v_lshl_add_u64 v[40:41], v[40:41], 2, s[12:13]
	v_lshl_add_u64 v[28:29], v[8:9], 2, s[12:13]
	global_load_dword v8, v[26:27], off
	global_load_dword v80, v[38:39], off
	global_load_dword v88, v[28:29], off
	global_load_dword v89, v[40:41], off
	s_add_i32 s27, s27, 16
	s_add_i32 s16, s16, 16
	s_add_i32 s28, s28, -16
	v_mad_u64_u32 v[26:27], s[42:43], v60, s36, v[6:7]
	s_cmp_lg_u32 s28, 0
	v_mad_u64_u32 v[28:29], s[42:43], v25, s36, v[6:7]
	v_mad_u64_u32 v[30:31], s[42:43], v62, s36, v[6:7]
	v_mad_u64_u32 v[32:33], s[42:43], v61, s36, v[6:7]
	v_mad_u64_u32 v[34:35], s[42:43], v64, s36, v[6:7]
	v_mad_u64_u32 v[36:37], s[42:43], v63, s36, v[6:7]
	v_mad_u64_u32 v[38:39], s[42:43], v66, s36, v[6:7]
	v_mad_u64_u32 v[40:41], s[42:43], v65, s36, v[6:7]
	v_mad_u64_u32 v[42:43], s[42:43], v68, s36, v[6:7]
	v_mad_u64_u32 v[58:59], s[42:43], v67, s36, v[6:7]
	v_mad_u64_u32 v[60:61], s[42:43], v70, s36, v[6:7]
	v_mad_u64_u32 v[62:63], s[42:43], v69, s36, v[6:7]
	v_mad_u64_u32 v[64:65], s[42:43], v72, s36, v[6:7]
	v_mad_u64_u32 v[66:67], s[42:43], v71, s36, v[6:7]
	v_mad_u64_u32 v[68:69], s[42:43], v74, s36, v[6:7]
	v_mad_u64_u32 v[70:71], s[42:43], v73, s36, v[6:7]
	v_mov_b32_e32 v109, v9
	s_lshl_b32 s29, s16, 1
	s_lshl_b32 s41, s27, 1
	v_or_b32_e32 v125, s29, v1
	v_or_b32_e32 v160, s41, v4
	s_add_i32 s43, s41, 4
	s_add_i32 s42, s29, 4
	s_add_i32 s44, s29, 8
	s_add_i32 s45, s41, 8
	s_add_i32 s46, s29, 12
	s_add_i32 s49, s29, 16
	s_add_i32 s51, s29, 20
	s_add_i32 s53, s29, 24
	s_add_i32 s29, s29, 28
	v_add_lshl_u32 v108, v125, s26, 10
	v_add_lshl_u32 v128, v160, s5, 10
	v_or_b32_e32 v162, s43, v4
	s_add_i32 s47, s41, 12
	v_or_b32_e32 v161, s42, v1
	v_or_b32_e32 v163, s44, v1
	v_or_b32_e32 v164, s45, v4
	v_or_b32_e32 v165, s46, v1
	v_or_b32_e32 v167, s49, v1
	v_or_b32_e32 v169, s51, v1
	v_or_b32_e32 v171, s53, v1
	v_or_b32_e32 v173, s29, v1
	v_or_b32_e32 v126, v5, v108
	v_or_b32_e32 v108, v24, v128
	v_add_lshl_u32 v130, v162, s5, 10
	v_mov_b32_e32 v127, v109
	s_add_i32 s50, s41, 16
	v_or_b32_e32 v166, s47, v4
	v_add_lshl_u32 v128, v161, s26, 10
	v_add_lshl_u32 v132, v163, s26, 10
	v_add_lshl_u32 v175, v164, s5, 10
	v_add_lshl_u32 v134, v165, s26, 10
	v_add_lshl_u32 v136, v167, s26, 10
	v_add_lshl_u32 v138, v169, s26, 10
	v_add_lshl_u32 v140, v171, s26, 10
	v_add_lshl_u32 v158, v173, s26, 10
	v_lshl_add_u64 v[142:143], v[108:109], 2, s[12:13]
	v_or_b32_e32 v108, v24, v130
	v_mov_b32_e32 v129, v109
	s_add_i32 s52, s41, 20
	v_or_b32_e32 v168, s50, v4
	v_add_lshl_u32 v176, v166, s5, 10
	v_lshl_add_u64 v[126:127], v[126:127], 2, s[12:13]
	v_or_b32_e32 v128, v5, v128
	v_or_b32_e32 v130, v5, v132
	v_or_b32_e32 v132, v5, v134
	v_or_b32_e32 v134, v5, v136
	v_or_b32_e32 v136, v5, v138
	v_or_b32_e32 v138, v5, v140
	v_or_b32_e32 v140, v5, v158
	v_lshl_add_u64 v[158:159], v[108:109], 2, s[12:13]
	v_or_b32_e32 v108, v24, v175
	s_add_i32 s54, s41, 24
	v_or_b32_e32 v170, s52, v4
	v_add_lshl_u32 v177, v168, s5, 10
	v_lshl_add_u64 v[128:129], v[128:129], 2, s[12:13]
	global_load_dword v175, v[142:143], off
	global_load_dword v181, v[126:127], off
	global_load_dword v182, v[158:159], off
	global_load_dword v183, v[128:129], off
	v_lshl_add_u64 v[126:127], v[108:109], 2, s[12:13]
	v_or_b32_e32 v108, v24, v176
	v_mov_b32_e32 v131, v109
	v_mov_b32_e32 v133, v109
	s_add_i32 s41, s41, 28
	v_or_b32_e32 v172, s54, v4
	v_add_lshl_u32 v178, v170, s5, 10
	v_lshl_add_u64 v[128:129], v[108:109], 2, s[12:13]
	v_or_b32_e32 v108, v24, v177
	v_or_b32_e32 v174, s41, v4
	v_add_lshl_u32 v179, v172, s5, 10
	v_lshl_add_u64 v[130:131], v[130:131], 2, s[12:13]
	v_lshl_add_u64 v[132:133], v[132:133], 2, s[12:13]
	global_load_dword v176, v[126:127], off
	global_load_dword v177, v[130:131], off
	global_load_dword v184, v[128:129], off
	global_load_dword v185, v[132:133], off
	v_lshl_add_u64 v[126:127], v[108:109], 2, s[12:13]
	v_or_b32_e32 v108, v24, v178
	v_mov_b32_e32 v135, v109
	v_mov_b32_e32 v137, v109
	v_add_lshl_u32 v180, v174, s5, 10
	v_lshl_add_u64 v[128:129], v[108:109], 2, s[12:13]
	v_or_b32_e32 v108, v24, v179
	v_mov_b32_e32 v139, v109
	v_mov_b32_e32 v141, v109
	v_lshl_add_u64 v[134:135], v[134:135], 2, s[12:13]
	v_lshl_add_u64 v[136:137], v[136:137], 2, s[12:13]
	global_load_dword v178, v[126:127], off
	global_load_dword v179, v[134:135], off
	global_load_dword v186, v[128:129], off
	global_load_dword v187, v[136:137], off
	v_lshl_add_u64 v[126:127], v[108:109], 2, s[12:13]
	v_or_b32_e32 v108, v24, v180
	v_lshl_add_u64 v[138:139], v[138:139], 2, s[12:13]
	v_lshl_add_u64 v[140:141], v[140:141], 2, s[12:13]
	v_lshl_add_u64 v[128:129], v[108:109], 2, s[12:13]
	global_load_dword v108, v[126:127], off
	global_load_dword v180, v[138:139], off
	global_load_dword v188, v[128:129], off
	global_load_dword v189, v[140:141], off
	s_add_i32 s27, s27, 16
	s_add_i32 s16, s16, 16
	s_add_i32 s28, s28, -16
	v_mad_u64_u32 v[126:127], s[42:43], v160, s36, v[6:7]
	s_cmp_lg_u32 s28, 0
	v_mad_u64_u32 v[128:129], s[42:43], v125, s36, v[6:7]
	v_mad_u64_u32 v[130:131], s[42:43], v162, s36, v[6:7]
	v_mad_u64_u32 v[132:133], s[42:43], v161, s36, v[6:7]
	v_mad_u64_u32 v[134:135], s[42:43], v164, s36, v[6:7]
	v_mad_u64_u32 v[136:137], s[42:43], v163, s36, v[6:7]
	v_mad_u64_u32 v[138:139], s[42:43], v166, s36, v[6:7]
	v_mad_u64_u32 v[140:141], s[42:43], v165, s36, v[6:7]
	v_mad_u64_u32 v[142:143], s[42:43], v168, s36, v[6:7]
	v_mad_u64_u32 v[158:159], s[42:43], v167, s36, v[6:7]
	v_mad_u64_u32 v[160:161], s[42:43], v170, s36, v[6:7]
	v_mad_u64_u32 v[162:163], s[42:43], v169, s36, v[6:7]
	v_mad_u64_u32 v[164:165], s[42:43], v172, s36, v[6:7]
	v_mad_u64_u32 v[166:167], s[42:43], v171, s36, v[6:7]
	v_mad_u64_u32 v[168:169], s[42:43], v174, s36, v[6:7]
	v_mad_u64_u32 v[170:171], s[42:43], v173, s36, v[6:7]
	s_waitcnt vmcnt(31)
	ds_write_b32 v26, v75
	s_waitcnt vmcnt(30)
	ds_write_b32 v28, v81
	s_waitcnt vmcnt(29)
	ds_write_b32 v30, v82
	s_waitcnt vmcnt(28)
	ds_write_b32 v32, v83
	s_waitcnt vmcnt(27)
	ds_write_b32 v34, v76
	s_waitcnt vmcnt(26)
	ds_write_b32 v36, v77
	s_waitcnt vmcnt(25)
	ds_write_b32 v38, v84
	s_waitcnt vmcnt(24)
	ds_write_b32 v40, v85
	s_waitcnt vmcnt(23)
	ds_write_b32 v42, v78
	s_waitcnt vmcnt(22)
	ds_write_b32 v58, v79
	s_waitcnt vmcnt(21)
	ds_write_b32 v60, v86
	s_waitcnt vmcnt(20)
	ds_write_b32 v62, v87
	s_waitcnt vmcnt(19)
	ds_write_b32 v64, v8
	s_waitcnt vmcnt(18)
	ds_write_b32 v66, v80
	s_waitcnt vmcnt(17)
	ds_write_b32 v68, v88
	s_waitcnt vmcnt(16)
	ds_write_b32 v70, v89
	s_waitcnt vmcnt(15)
	ds_write_b32 v126, v175
	s_waitcnt vmcnt(14)
	ds_write_b32 v128, v181
	s_waitcnt vmcnt(13)
	ds_write_b32 v130, v182
	s_waitcnt vmcnt(12)
	ds_write_b32 v132, v183
	s_waitcnt vmcnt(11)
	ds_write_b32 v134, v176
	s_waitcnt vmcnt(10)
	ds_write_b32 v136, v177
	s_waitcnt vmcnt(9)
	ds_write_b32 v138, v184
	s_waitcnt vmcnt(8)
	ds_write_b32 v140, v185
	s_waitcnt vmcnt(7)
	ds_write_b32 v142, v178
	s_waitcnt vmcnt(6)
	ds_write_b32 v158, v179
	s_waitcnt vmcnt(5)
	ds_write_b32 v160, v186
	s_waitcnt vmcnt(4)
	ds_write_b32 v162, v187
	s_waitcnt vmcnt(3)
	ds_write_b32 v164, v108
	s_waitcnt vmcnt(2)
	ds_write_b32 v166, v180
	s_waitcnt vmcnt(1)
	ds_write_b32 v168, v188
	s_waitcnt vmcnt(0)
	ds_write_b32 v170, v189
	s_cbranch_scc1 .LBB0_51
	s_waitcnt lgkmcnt(0)
	ds_read2_b32 v[28:29], v46 offset0:33 offset1:41
	ds_read2_b32 v[30:31], v46 offset1:8
	ds_read2_b32 v[32:33], v46 offset0:66 offset1:74
	ds_read2_b32 v[34:35], v46 offset0:99 offset1:107
	ds_read2_b32 v[36:37], v46 offset0:132 offset1:140
	ds_read2_b32 v[38:39], v46 offset0:165 offset1:173
	ds_read2_b32 v[40:41], v46 offset0:198 offset1:206
	ds_read2_b32 v[42:43], v46 offset0:231 offset1:239
	s_lshl_b32 s16, s5, 1
	v_or_b32_e32 v5, s4, v45
	v_lshl_add_u64 v[58:59], v[18:19], 0, s[16:17]
	v_lshlrev_b32_e32 v8, 11, v5
	s_waitcnt lgkmcnt(6)
	v_cvt_pk_bf16_f32 v24, v30, v28
	s_waitcnt lgkmcnt(4)
	v_cvt_pk_bf16_f32 v25, v32, v34
	s_waitcnt lgkmcnt(2)
	v_cvt_pk_bf16_f32 v26, v36, v38
	s_waitcnt lgkmcnt(0)
	v_cvt_pk_bf16_f32 v27, v40, v42
	v_lshl_add_u64 v[60:61], v[58:59], 0, v[8:9]
	global_store_dwordx4 v[60:61], v[24:27], off
	v_or_b32_e32 v5, s4, v47
	v_lshlrev_b32_e32 v8, 11, v5
	v_cvt_pk_bf16_f32 v24, v31, v29
	v_cvt_pk_bf16_f32 v25, v33, v35
	v_cvt_pk_bf16_f32 v26, v37, v39
	v_cvt_pk_bf16_f32 v27, v41, v43
	ds_read2_b32 v[30:31], v46 offset0:49 offset1:57
	ds_read2_b32 v[32:33], v46 offset0:16 offset1:24
	ds_read2_b32 v[34:35], v46 offset0:82 offset1:90
	ds_read2_b32 v[36:37], v46 offset0:115 offset1:123
	ds_read2_b32 v[38:39], v46 offset0:148 offset1:156
	ds_read2_b32 v[40:41], v46 offset0:181 offset1:189
	ds_read2_b32 v[42:43], v46 offset0:214 offset1:222
	ds_read2_b32 v[60:61], v46 offset0:247 offset1:255
	v_or_b32_e32 v5, s4, v48
	v_lshl_add_u64 v[28:29], v[58:59], 0, v[8:9]
	v_lshlrev_b32_e32 v8, 11, v5
	v_or_b32_e32 v5, s4, v49
	global_store_dwordx4 v[28:29], v[24:27], off
	v_lshl_add_u64 v[28:29], v[58:59], 0, v[8:9]
	v_lshlrev_b32_e32 v8, 11, v5
	s_waitcnt lgkmcnt(6)
	v_cvt_pk_bf16_f32 v24, v32, v30
	s_waitcnt lgkmcnt(4)
	v_cvt_pk_bf16_f32 v25, v34, v36
	s_waitcnt lgkmcnt(2)
	v_cvt_pk_bf16_f32 v26, v38, v40
	s_waitcnt lgkmcnt(0)
	v_cvt_pk_bf16_f32 v27, v42, v60
	global_store_dwordx4 v[28:29], v[24:27], off
	v_lshl_add_u64 v[28:29], v[58:59], 0, v[8:9]
	s_nop 0
	v_cvt_pk_bf16_f32 v24, v33, v31
	v_cvt_pk_bf16_f32 v25, v35, v37
	v_cvt_pk_bf16_f32 v26, v39, v41
	v_cvt_pk_bf16_f32 v27, v43, v61
	global_store_dwordx4 v[28:29], v[24:27], off
	s_waitcnt lgkmcnt(0)

.LBB0_60:
	s_lshl_b32 s41, s5, 1
	s_lshl_b32 s42, s26, 1
	v_or_b32_e32 v26, s42, v8
	s_add_i32 s43, s41, 4
	s_add_i32 s44, s42, 4
	s_add_i32 s45, s41, 8
	s_add_i32 s46, s42, 8
	s_add_i32 s47, s41, 12
	s_add_i32 s49, s42, 12
	s_add_i32 s50, s41, 16
	s_add_i32 s51, s42, 16
	s_add_i32 s52, s41, 20
	s_add_i32 s53, s42, 20
	s_add_i32 s54, s41, 24
	s_add_i32 s55, s42, 24
	s_add_i32 s56, s41, 28
	s_add_i32 s57, s42, 28
	v_or_b32_e32 v28, s41, v5
	v_mad_i64_i32 v[26:27], s[28:29], v26, s39, v[24:25]
	v_or_b32_e32 v32, s43, v5
	v_or_b32_e32 v30, s44, v8
	v_or_b32_e32 v36, s45, v5
	v_or_b32_e32 v34, s46, v8
	v_or_b32_e32 v40, s47, v5
	v_or_b32_e32 v38, s49, v8
	v_or_b32_e32 v58, s50, v5
	v_or_b32_e32 v42, s51, v8
	v_or_b32_e32 v62, s52, v5
	v_or_b32_e32 v60, s53, v8
	v_or_b32_e32 v66, s54, v5
	v_or_b32_e32 v64, s55, v8
	v_or_b32_e32 v70, s56, v5
	v_or_b32_e32 v68, s57, v8
	v_mad_i64_i32 v[28:29], s[28:29], v28, s39, v[24:25]
	v_mad_i64_i32 v[30:31], s[28:29], v30, s39, v[24:25]
	v_mad_i64_i32 v[32:33], s[28:29], v32, s39, v[24:25]
	v_mad_i64_i32 v[34:35], s[28:29], v34, s39, v[24:25]
	v_mad_i64_i32 v[36:37], s[28:29], v36, s39, v[24:25]
	v_mad_i64_i32 v[38:39], s[28:29], v38, s39, v[24:25]
	v_mad_i64_i32 v[40:41], s[28:29], v40, s39, v[24:25]
	v_mad_i64_i32 v[42:43], s[28:29], v42, s39, v[24:25]
	v_mad_i64_i32 v[58:59], s[28:29], v58, s39, v[24:25]
	v_mad_i64_i32 v[60:61], s[28:29], v60, s39, v[24:25]
	v_mad_i64_i32 v[62:63], s[28:29], v62, s39, v[24:25]
	v_mad_i64_i32 v[64:65], s[28:29], v64, s39, v[24:25]
	v_mad_i64_i32 v[66:67], s[28:29], v66, s39, v[24:25]
	v_mad_i64_i32 v[68:69], s[28:29], v68, s39, v[24:25]
	v_mad_i64_i32 v[70:71], s[28:29], v70, s39, v[24:25]
	global_load_dword v72, v[26:27], off
	global_load_dword v73, v[28:29], off
	global_load_dword v74, v[30:31], off
	global_load_dword v75, v[32:33], off
	global_load_dword v76, v[34:35], off
	global_load_dword v77, v[36:37], off
	global_load_dword v78, v[38:39], off
	global_load_dword v79, v[40:41], off
	global_load_dword v80, v[42:43], off
	global_load_dword v81, v[58:59], off
	global_load_dword v82, v[60:61], off
	global_load_dword v83, v[62:63], off
	global_load_dword v84, v[64:65], off
	global_load_dword v85, v[66:67], off
	global_load_dword v86, v[68:69], off
	global_load_dword v87, v[70:71], off
	v_or_b32_e32 v28, s41, v1
	v_or_b32_e32 v26, s42, v4
	s_add_i32 s26, s26, 16
	s_add_i32 s5, s5, 16
	s_add_i32 s27, s27, -16
	v_mad_u64_u32 v[26:27], s[28:29], v26, s36, v[6:7]
	v_mad_u64_u32 v[28:29], s[28:29], v28, s36, v[6:7]
	v_or_b32_e32 v27, s43, v1
	v_or_b32_e32 v29, s44, v4
	v_or_b32_e32 v36, s45, v1
	v_or_b32_e32 v34, s46, v4
	v_or_b32_e32 v40, s47, v1
	v_or_b32_e32 v38, s49, v4
	v_or_b32_e32 v58, s50, v1
	v_or_b32_e32 v42, s51, v4
	v_or_b32_e32 v62, s52, v1
	v_or_b32_e32 v60, s53, v4
	v_or_b32_e32 v66, s54, v1
	v_or_b32_e32 v64, s55, v4
	v_or_b32_e32 v70, s56, v1
	v_or_b32_e32 v68, s57, v4
	s_cmp_lg_u32 s27, 0
	v_mad_u64_u32 v[30:31], s[28:29], v29, s36, v[6:7]
	v_mad_u64_u32 v[32:33], s[28:29], v27, s36, v[6:7]
	v_mad_u64_u32 v[34:35], s[28:29], v34, s36, v[6:7]
	v_mad_u64_u32 v[36:37], s[28:29], v36, s36, v[6:7]
	v_mad_u64_u32 v[38:39], s[28:29], v38, s36, v[6:7]
	v_mad_u64_u32 v[40:41], s[28:29], v40, s36, v[6:7]
	v_mad_u64_u32 v[42:43], s[28:29], v42, s36, v[6:7]
	v_mad_u64_u32 v[58:59], s[28:29], v58, s36, v[6:7]
	v_mad_u64_u32 v[60:61], s[28:29], v60, s36, v[6:7]
	v_mad_u64_u32 v[62:63], s[28:29], v62, s36, v[6:7]
	v_mad_u64_u32 v[64:65], s[28:29], v64, s36, v[6:7]
	v_mad_u64_u32 v[66:67], s[28:29], v66, s36, v[6:7]
	v_mad_u64_u32 v[68:69], s[28:29], v68, s36, v[6:7]
	v_mad_u64_u32 v[70:71], s[28:29], v70, s36, v[6:7]
	s_lshl_b32 s41, s5, 1
	s_lshl_b32 s42, s26, 1
	v_or_b32_e32 v126, s42, v8
	s_add_i32 s43, s41, 4
	s_add_i32 s44, s42, 4
	s_add_i32 s45, s41, 8
	s_add_i32 s46, s42, 8
	s_add_i32 s47, s41, 12
	s_add_i32 s49, s42, 12
	s_add_i32 s50, s41, 16
	s_add_i32 s51, s42, 16
	s_add_i32 s52, s41, 20
	s_add_i32 s53, s42, 20
	s_add_i32 s54, s41, 24
	s_add_i32 s55, s42, 24
	s_add_i32 s56, s41, 28
	s_add_i32 s57, s42, 28
	v_or_b32_e32 v128, s41, v5
	v_mad_i64_i32 v[126:127], s[28:29], v126, s39, v[24:25]
	v_or_b32_e32 v132, s43, v5
	v_or_b32_e32 v130, s44, v8
	v_or_b32_e32 v136, s45, v5
	v_or_b32_e32 v134, s46, v8
	v_or_b32_e32 v140, s47, v5
	v_or_b32_e32 v138, s49, v8
	v_or_b32_e32 v158, s50, v5
	v_or_b32_e32 v142, s51, v8
	v_or_b32_e32 v162, s52, v5
	v_or_b32_e32 v160, s53, v8
	v_or_b32_e32 v166, s54, v5
	v_or_b32_e32 v164, s55, v8
	v_or_b32_e32 v170, s56, v5
	v_or_b32_e32 v168, s57, v8
	v_mad_i64_i32 v[128:129], s[28:29], v128, s39, v[24:25]
	v_mad_i64_i32 v[130:131], s[28:29], v130, s39, v[24:25]
	v_mad_i64_i32 v[132:133], s[28:29], v132, s39, v[24:25]
	v_mad_i64_i32 v[134:135], s[28:29], v134, s39, v[24:25]
	v_mad_i64_i32 v[136:137], s[28:29], v136, s39, v[24:25]
	v_mad_i64_i32 v[138:139], s[28:29], v138, s39, v[24:25]
	v_mad_i64_i32 v[140:141], s[28:29], v140, s39, v[24:25]
	v_mad_i64_i32 v[142:143], s[28:29], v142, s39, v[24:25]
	v_mad_i64_i32 v[158:159], s[28:29], v158, s39, v[24:25]
	v_mad_i64_i32 v[160:161], s[28:29], v160, s39, v[24:25]
	v_mad_i64_i32 v[162:163], s[28:29], v162, s39, v[24:25]
	v_mad_i64_i32 v[164:165], s[28:29], v164, s39, v[24:25]
	v_mad_i64_i32 v[166:167], s[28:29], v166, s39, v[24:25]
	v_mad_i64_i32 v[168:169], s[28:29], v168, s39, v[24:25]
	v_mad_i64_i32 v[170:171], s[28:29], v170, s39, v[24:25]
	global_load_dword v172, v[126:127], off
	global_load_dword v173, v[128:129], off
	global_load_dword v174, v[130:131], off
	global_load_dword v175, v[132:133], off
	global_load_dword v176, v[134:135], off
	global_load_dword v177, v[136:137], off
	global_load_dword v178, v[138:139], off
	global_load_dword v179, v[140:141], off
	global_load_dword v180, v[142:143], off
	global_load_dword v181, v[158:159], off
	global_load_dword v182, v[160:161], off
	global_load_dword v183, v[162:163], off
	global_load_dword v184, v[164:165], off
	global_load_dword v185, v[166:167], off
	global_load_dword v186, v[168:169], off
	global_load_dword v187, v[170:171], off
	v_or_b32_e32 v128, s41, v1
	v_or_b32_e32 v126, s42, v4
	s_add_i32 s26, s26, 16
	s_add_i32 s5, s5, 16
	s_add_i32 s27, s27, -16
	v_mad_u64_u32 v[126:127], s[28:29], v126, s36, v[6:7]
	v_mad_u64_u32 v[128:129], s[28:29], v128, s36, v[6:7]
	v_or_b32_e32 v127, s43, v1
	v_or_b32_e32 v129, s44, v4
	v_or_b32_e32 v136, s45, v1
	v_or_b32_e32 v134, s46, v4
	v_or_b32_e32 v140, s47, v1
	v_or_b32_e32 v138, s49, v4
	v_or_b32_e32 v158, s50, v1
	v_or_b32_e32 v142, s51, v4
	v_or_b32_e32 v162, s52, v1
	v_or_b32_e32 v160, s53, v4
	v_or_b32_e32 v166, s54, v1
	v_or_b32_e32 v164, s55, v4
	v_or_b32_e32 v170, s56, v1
	v_or_b32_e32 v168, s57, v4
	s_cmp_lg_u32 s27, 0
	v_mad_u64_u32 v[130:131], s[28:29], v129, s36, v[6:7]
	v_mad_u64_u32 v[132:133], s[28:29], v127, s36, v[6:7]
	v_mad_u64_u32 v[134:135], s[28:29], v134, s36, v[6:7]
	v_mad_u64_u32 v[136:137], s[28:29], v136, s36, v[6:7]
	v_mad_u64_u32 v[138:139], s[28:29], v138, s36, v[6:7]
	v_mad_u64_u32 v[140:141], s[28:29], v140, s36, v[6:7]
	v_mad_u64_u32 v[142:143], s[28:29], v142, s36, v[6:7]
	v_mad_u64_u32 v[158:159], s[28:29], v158, s36, v[6:7]
	v_mad_u64_u32 v[160:161], s[28:29], v160, s36, v[6:7]
	v_mad_u64_u32 v[162:163], s[28:29], v162, s36, v[6:7]
	v_mad_u64_u32 v[164:165], s[28:29], v164, s36, v[6:7]
	v_mad_u64_u32 v[166:167], s[28:29], v166, s36, v[6:7]
	v_mad_u64_u32 v[168:169], s[28:29], v168, s36, v[6:7]
	v_mad_u64_u32 v[170:171], s[28:29], v170, s36, v[6:7]
	s_waitcnt vmcnt(31)
	ds_write_b32 v26, v72
	s_waitcnt vmcnt(30)
	ds_write_b32 v28, v73
	s_waitcnt vmcnt(29)
	ds_write_b32 v30, v74
	s_waitcnt vmcnt(28)
	ds_write_b32 v32, v75
	s_waitcnt vmcnt(27)
	ds_write_b32 v34, v76
	s_waitcnt vmcnt(26)
	ds_write_b32 v36, v77
	s_waitcnt vmcnt(25)
	ds_write_b32 v38, v78
	s_waitcnt vmcnt(24)
	ds_write_b32 v40, v79
	s_waitcnt vmcnt(23)
	ds_write_b32 v42, v80
	s_waitcnt vmcnt(22)
	ds_write_b32 v58, v81
	s_waitcnt vmcnt(21)
	ds_write_b32 v60, v82
	s_waitcnt vmcnt(20)
	ds_write_b32 v62, v83
	s_waitcnt vmcnt(19)
	ds_write_b32 v64, v84
	s_waitcnt vmcnt(18)
	ds_write_b32 v66, v85
	s_waitcnt vmcnt(17)
	ds_write_b32 v68, v86
	s_waitcnt vmcnt(16)
	ds_write_b32 v70, v87
	s_waitcnt vmcnt(15)
	ds_write_b32 v126, v172
	s_waitcnt vmcnt(14)
	ds_write_b32 v128, v173
	s_waitcnt vmcnt(13)
	ds_write_b32 v130, v174
	s_waitcnt vmcnt(12)
	ds_write_b32 v132, v175
	s_waitcnt vmcnt(11)
	ds_write_b32 v134, v176
	s_waitcnt vmcnt(10)
	ds_write_b32 v136, v177
	s_waitcnt vmcnt(9)
	ds_write_b32 v138, v178
	s_waitcnt vmcnt(8)
	ds_write_b32 v140, v179
	s_waitcnt vmcnt(7)
	ds_write_b32 v142, v180
	s_waitcnt vmcnt(6)
	ds_write_b32 v158, v181
	s_waitcnt vmcnt(5)
	ds_write_b32 v160, v182
	s_waitcnt vmcnt(4)
	ds_write_b32 v162, v183
	s_waitcnt vmcnt(3)
	ds_write_b32 v164, v184
	s_waitcnt vmcnt(2)
	ds_write_b32 v166, v185
	s_waitcnt vmcnt(1)
	ds_write_b32 v168, v186
	s_waitcnt vmcnt(0)
	ds_write_b32 v170, v187
	s_cbranch_scc1 .LBB0_60
	s_waitcnt lgkmcnt(0)
	ds_read2_b32 v[28:29], v46 offset0:33 offset1:41
	ds_read2_b32 v[30:31], v46 offset1:8
	ds_read2_b32 v[32:33], v46 offset0:66 offset1:74
	ds_read2_b32 v[34:35], v46 offset0:99 offset1:107
	ds_read2_b32 v[36:37], v46 offset0:132 offset1:140
	ds_read2_b32 v[38:39], v46 offset0:165 offset1:173
	ds_read2_b32 v[40:41], v46 offset0:198 offset1:206
	ds_read2_b32 v[42:43], v46 offset0:231 offset1:239
	v_or_b32_e32 v60, s16, v45
	s_ashr_i32 s5, s4, 31
	v_ashrrev_i32_e32 v61, 31, v60
	v_lshl_add_u64 v[58:59], s[4:5], 1, v[20:21]
	v_lshlrev_b64 v[60:61], 11, v[60:61]
	s_waitcnt lgkmcnt(6)
	v_cvt_pk_bf16_f32 v24, v30, v28
	s_waitcnt lgkmcnt(4)
	v_cvt_pk_bf16_f32 v25, v32, v34
	s_waitcnt lgkmcnt(2)
	v_cvt_pk_bf16_f32 v26, v36, v38
	s_waitcnt lgkmcnt(0)
	v_cvt_pk_bf16_f32 v27, v40, v42
	v_lshl_add_u64 v[60:61], v[58:59], 0, v[60:61]
	v_or_b32_e32 v28, s16, v47
	global_store_dwordx4 v[60:61], v[24:27], off
	s_nop 1
	v_cvt_pk_bf16_f32 v24, v31, v29
	v_ashrrev_i32_e32 v29, 31, v28
	v_cvt_pk_bf16_f32 v25, v33, v35
	v_cvt_pk_bf16_f32 v26, v37, v39
	v_cvt_pk_bf16_f32 v27, v41, v43
	v_lshlrev_b64 v[28:29], 11, v[28:29]
	ds_read2_b32 v[30:31], v46 offset0:49 offset1:57
	ds_read2_b32 v[32:33], v46 offset0:16 offset1:24
	ds_read2_b32 v[34:35], v46 offset0:82 offset1:90
	ds_read2_b32 v[36:37], v46 offset0:115 offset1:123
	ds_read2_b32 v[38:39], v46 offset0:148 offset1:156
	ds_read2_b32 v[40:41], v46 offset0:181 offset1:189
	ds_read2_b32 v[42:43], v46 offset0:214 offset1:222
	ds_read2_b32 v[60:61], v46 offset0:247 offset1:255
	v_lshl_add_u64 v[28:29], v[58:59], 0, v[28:29]
	global_store_dwordx4 v[28:29], v[24:27], off
	v_or_b32_e32 v28, s16, v48
	v_ashrrev_i32_e32 v29, 31, v28
	v_lshlrev_b64 v[28:29], 11, v[28:29]
	s_waitcnt lgkmcnt(6)
	v_cvt_pk_bf16_f32 v24, v32, v30
	s_waitcnt lgkmcnt(4)
	v_cvt_pk_bf16_f32 v25, v34, v36
	s_waitcnt lgkmcnt(2)
	v_cvt_pk_bf16_f32 v26, v38, v40
	s_waitcnt lgkmcnt(0)
	v_cvt_pk_bf16_f32 v27, v42, v60
	v_lshl_add_u64 v[28:29], v[58:59], 0, v[28:29]
	global_store_dwordx4 v[28:29], v[24:27], off
	v_or_b32_e32 v28, s16, v49
	v_ashrrev_i32_e32 v29, 31, v28
	v_lshlrev_b64 v[28:29], 11, v[28:29]
	v_cvt_pk_bf16_f32 v24, v33, v31
	v_cvt_pk_bf16_f32 v25, v35, v37
	v_cvt_pk_bf16_f32 v26, v39, v41
	v_cvt_pk_bf16_f32 v27, v43, v61
	v_lshl_add_u64 v[28:29], v[58:59], 0, v[28:29]
	global_store_dwordx4 v[28:29], v[24:27], off
	s_waitcnt lgkmcnt(0)
	s_branch .LBB0_8
